# scan waves: k^d read four steps ahead (others three) so one wait per two steps leaves a full step of LDS latency slack; spread staging bursts as before
# baseline (speedup 1.0000x reference)
.Lsc_S_go:
	ds_read_b128 v[144:147], v34 offset:32768
	ds_read_b128 v[156:159], v35 offset:0
	ds_read_b128 v[76:79], v34 offset:0
	ds_read_b128 v[80:83], v34 offset:256
	ds_read_b128 v[84:87], v34 offset:512
	ds_read_b128 v[88:91], v34 offset:768
	ds_read_b128 v[92:95], v34 offset:1024
	ds_read_b128 v[96:99], v34 offset:1280
	ds_read_b128 v[100:103], v34 offset:1536
	ds_read_b128 v[104:107], v34 offset:1792
	ds_read_b128 v[124:127], v34 offset:3072
	s_waitcnt lgkmcnt(10)
	v_pk_mul_f32 v[24:25], v[10:11], v[144:145]
	v_pk_fma_f32 v[24:25], v[8:9], v[146:147], v[24:25]
	v_add_f32_e32 v24, v24, v25
	s_waitcnt lgkmcnt(8)
	v_pk_fma_f32 v[16:17], v[76:77], v[156:157], v[10:11] op_sel_hi:[1,0,1]
	v_pk_fma_f32 v[18:19], v[78:79], v[156:157], v[8:9] op_sel_hi:[1,0,1]
	v_add_f32_dpp v15, v24, v24 row_ror:8 row_mask:0xf bank_mask:0xf bound_ctrl:1
	ds_read_b128 v[108:111], v34 offset:2048
	ds_read_b128 v[112:115], v34 offset:2304
	v_add_f32_dpp v15, v15, v15 row_ror:4 row_mask:0xf bank_mask:0xf bound_ctrl:1
	ds_read_b128 v[116:119], v34 offset:2560
	ds_read_b128 v[120:123], v34 offset:2816
	v_add_f32_dpp v15, v15, v15 row_ror:2 row_mask:0xf bank_mask:0xf bound_ctrl:1
	s_nop 1
	v_add_f32_dpp v30, v15, v15 row_ror:1 row_mask:0xf bank_mask:0xf bound_ctrl:1
	s_waitcnt lgkmcnt(0)
.Lsc_S_loop:
	s_waitcnt lgkmcnt(4)
	v_pk_fma_f32 v[10:11], v[80:81], v[30:31], v[16:17] op_sel_hi:[1,0,1] neg_lo:[0,1,0] neg_hi:[0,1,0]
	v_pk_fma_f32 v[8:9], v[82:83], v[30:31], v[18:19] op_sel_hi:[1,0,1] neg_lo:[0,1,0] neg_hi:[0,1,0]
	v_pk_mul_f32 v[24:25], v[10:11], v[84:85] op_sel:[0,0] op_sel_hi:[0,1]
	v_pk_fma_f32 v[24:25], v[10:11], v[86:87], v[24:25] op_sel:[1,0,0] op_sel_hi:[1,1,1]
	v_pk_fma_f32 v[24:25], v[8:9], v[88:89], v[24:25] op_sel:[0,0,0] op_sel_hi:[0,1,1]
	v_pk_fma_f32 v[24:25], v[8:9], v[90:91], v[24:25] op_sel:[1,0,0] op_sel_hi:[1,1,1]
	v_pk_fma_f32 v[16:17], v[92:93], v[156:157], v[10:11] op_sel:[0,1,0] op_sel_hi:[1,1,1]
	v_pk_fma_f32 v[18:19], v[94:95], v[156:157], v[8:9] op_sel:[0,1,0] op_sel_hi:[1,1,1]
	v_add_f32_dpp v15, v24, v24 row_ror:8 row_mask:0xf bank_mask:0xf bound_ctrl:1
	ds_read_b128 v[76:79], v34 offset:4096
	s_nop 0
	v_add_f32_dpp v15, v15, v15 row_ror:4 row_mask:0xf bank_mask:0xf bound_ctrl:1
	ds_read_b128 v[128:131], v34 offset:3328
	ds_read_b128 v[132:135], v34 offset:3584
	v_add_f32_dpp v15, v15, v15 row_ror:2 row_mask:0xf bank_mask:0xf bound_ctrl:1
	ds_read_b128 v[136:139], v34 offset:3840
	ds_read_b128 v[160:163], v35 offset:16
	v_add_f32_dpp v30, v15, v15 row_ror:1 row_mask:0xf bank_mask:0xf bound_ctrl:1
	v_pk_fma_f32 v[10:11], v[96:97], v[30:31], v[16:17] op_sel_hi:[1,0,1] neg_lo:[0,1,0] neg_hi:[0,1,0]
	v_pk_fma_f32 v[8:9], v[98:99], v[30:31], v[18:19] op_sel_hi:[1,0,1] neg_lo:[0,1,0] neg_hi:[0,1,0]
	v_pk_mul_f32 v[26:27], v[10:11], v[100:101] op_sel:[0,0] op_sel_hi:[0,1]
	v_pk_fma_f32 v[26:27], v[10:11], v[102:103], v[26:27] op_sel:[1,0,0] op_sel_hi:[1,1,1]
	v_pk_fma_f32 v[26:27], v[8:9], v[104:105], v[26:27] op_sel:[0,0,0] op_sel_hi:[0,1,1]
	v_pk_fma_f32 v[26:27], v[8:9], v[106:107], v[26:27] op_sel:[1,0,0] op_sel_hi:[1,1,1]
	v_pk_fma_f32 v[16:17], v[108:109], v[158:159], v[10:11] op_sel_hi:[1,0,1]
	v_pk_fma_f32 v[18:19], v[110:111], v[158:159], v[8:9] op_sel_hi:[1,0,1]
	v_add_f32_dpp v15, v26, v26 row_ror:8 row_mask:0xf bank_mask:0xf bound_ctrl:1
	ds_read_b128 v[92:95], v34 offset:5120
	s_nop 0
	v_add_f32_dpp v15, v15, v15 row_ror:4 row_mask:0xf bank_mask:0xf bound_ctrl:1
	ds_read_b128 v[80:83], v34 offset:4352
	ds_read_b128 v[84:87], v34 offset:4608
	v_add_f32_dpp v15, v15, v15 row_ror:2 row_mask:0xf bank_mask:0xf bound_ctrl:1
	ds_read_b128 v[88:91], v34 offset:4864
	ds_write2st64_b32 v37, v25, v27 offset0:0 offset1:4
	v_add_f32_dpp v30, v15, v15 row_ror:1 row_mask:0xf bank_mask:0xf bound_ctrl:1
	s_waitcnt lgkmcnt(5)
	v_pk_fma_f32 v[10:11], v[112:113], v[30:31], v[16:17] op_sel_hi:[1,0,1] neg_lo:[0,1,0] neg_hi:[0,1,0]
	v_pk_fma_f32 v[8:9], v[114:115], v[30:31], v[18:19] op_sel_hi:[1,0,1] neg_lo:[0,1,0] neg_hi:[0,1,0]
	v_pk_mul_f32 v[24:25], v[10:11], v[116:117] op_sel:[0,0] op_sel_hi:[0,1]
	v_pk_fma_f32 v[24:25], v[10:11], v[118:119], v[24:25] op_sel:[1,0,0] op_sel_hi:[1,1,1]
	v_pk_fma_f32 v[24:25], v[8:9], v[120:121], v[24:25] op_sel:[0,0,0] op_sel_hi:[0,1,1]
	v_pk_fma_f32 v[24:25], v[8:9], v[122:123], v[24:25] op_sel:[1,0,0] op_sel_hi:[1,1,1]
	v_pk_fma_f32 v[16:17], v[124:125], v[158:159], v[10:11] op_sel:[0,1,0] op_sel_hi:[1,1,1]
	v_pk_fma_f32 v[18:19], v[126:127], v[158:159], v[8:9] op_sel:[0,1,0] op_sel_hi:[1,1,1]
	v_add_f32_dpp v15, v24, v24 row_ror:8 row_mask:0xf bank_mask:0xf bound_ctrl:1
	ds_read_b128 v[108:111], v34 offset:6144
	s_nop 0
	v_add_f32_dpp v15, v15, v15 row_ror:4 row_mask:0xf bank_mask:0xf bound_ctrl:1
	ds_read_b128 v[96:99], v34 offset:5376
	ds_read_b128 v[100:103], v34 offset:5632
	v_add_f32_dpp v15, v15, v15 row_ror:2 row_mask:0xf bank_mask:0xf bound_ctrl:1
	ds_read_b128 v[104:107], v34 offset:5888
	s_nop 0
	v_add_f32_dpp v30, v15, v15 row_ror:1 row_mask:0xf bank_mask:0xf bound_ctrl:1
	v_pk_fma_f32 v[10:11], v[128:129], v[30:31], v[16:17] op_sel_hi:[1,0,1] neg_lo:[0,1,0] neg_hi:[0,1,0]
	v_pk_fma_f32 v[8:9], v[130:131], v[30:31], v[18:19] op_sel_hi:[1,0,1] neg_lo:[0,1,0] neg_hi:[0,1,0]
	v_pk_mul_f32 v[26:27], v[10:11], v[132:133] op_sel:[0,0] op_sel_hi:[0,1]
	v_pk_fma_f32 v[26:27], v[10:11], v[134:135], v[26:27] op_sel:[1,0,0] op_sel_hi:[1,1,1]
	v_pk_fma_f32 v[26:27], v[8:9], v[136:137], v[26:27] op_sel:[0,0,0] op_sel_hi:[0,1,1]
	v_pk_fma_f32 v[26:27], v[8:9], v[138:139], v[26:27] op_sel:[1,0,0] op_sel_hi:[1,1,1]
	v_pk_fma_f32 v[16:17], v[76:77], v[160:161], v[10:11] op_sel_hi:[1,0,1]
	v_pk_fma_f32 v[18:19], v[78:79], v[160:161], v[8:9] op_sel_hi:[1,0,1]
	v_add_f32_dpp v15, v26, v26 row_ror:8 row_mask:0xf bank_mask:0xf bound_ctrl:1
	ds_read_b128 v[124:127], v34 offset:7168
	s_nop 0
	v_add_f32_dpp v15, v15, v15 row_ror:4 row_mask:0xf bank_mask:0xf bound_ctrl:1
	ds_read_b128 v[112:115], v34 offset:6400
	ds_read_b128 v[116:119], v34 offset:6656
	v_add_f32_dpp v15, v15, v15 row_ror:2 row_mask:0xf bank_mask:0xf bound_ctrl:1
	ds_read_b128 v[120:123], v34 offset:6912
	ds_write2st64_b32 v37, v25, v27 offset0:8 offset1:12
	v_add_f32_dpp v30, v15, v15 row_ror:1 row_mask:0xf bank_mask:0xf bound_ctrl:1
	s_waitcnt lgkmcnt(5)
	v_pk_fma_f32 v[10:11], v[80:81], v[30:31], v[16:17] op_sel_hi:[1,0,1] neg_lo:[0,1,0] neg_hi:[0,1,0]
	v_pk_fma_f32 v[8:9], v[82:83], v[30:31], v[18:19] op_sel_hi:[1,0,1] neg_lo:[0,1,0] neg_hi:[0,1,0]
	v_pk_mul_f32 v[24:25], v[10:11], v[84:85] op_sel:[0,0] op_sel_hi:[0,1]
	v_pk_fma_f32 v[24:25], v[10:11], v[86:87], v[24:25] op_sel:[1,0,0] op_sel_hi:[1,1,1]
	v_pk_fma_f32 v[24:25], v[8:9], v[88:89], v[24:25] op_sel:[0,0,0] op_sel_hi:[0,1,1]
	v_pk_fma_f32 v[24:25], v[8:9], v[90:91], v[24:25] op_sel:[1,0,0] op_sel_hi:[1,1,1]
	v_pk_fma_f32 v[16:17], v[92:93], v[160:161], v[10:11] op_sel:[0,1,0] op_sel_hi:[1,1,1]
	v_pk_fma_f32 v[18:19], v[94:95], v[160:161], v[8:9] op_sel:[0,1,0] op_sel_hi:[1,1,1]
	v_add_f32_dpp v15, v24, v24 row_ror:8 row_mask:0xf bank_mask:0xf bound_ctrl:1
	ds_read_b128 v[76:79], v34 offset:8192
	s_nop 0
	v_add_f32_dpp v15, v15, v15 row_ror:4 row_mask:0xf bank_mask:0xf bound_ctrl:1
	ds_read_b128 v[128:131], v34 offset:7424
	ds_read_b128 v[132:135], v34 offset:7680
	v_add_f32_dpp v15, v15, v15 row_ror:2 row_mask:0xf bank_mask:0xf bound_ctrl:1
	ds_read_b128 v[136:139], v34 offset:7936
	ds_read_b128 v[156:159], v35 offset:32
	v_add_f32_dpp v30, v15, v15 row_ror:1 row_mask:0xf bank_mask:0xf bound_ctrl:1
	v_pk_fma_f32 v[10:11], v[96:97], v[30:31], v[16:17] op_sel_hi:[1,0,1] neg_lo:[0,1,0] neg_hi:[0,1,0]
	v_pk_fma_f32 v[8:9], v[98:99], v[30:31], v[18:19] op_sel_hi:[1,0,1] neg_lo:[0,1,0] neg_hi:[0,1,0]
	v_pk_mul_f32 v[26:27], v[10:11], v[100:101] op_sel:[0,0] op_sel_hi:[0,1]
	v_pk_fma_f32 v[26:27], v[10:11], v[102:103], v[26:27] op_sel:[1,0,0] op_sel_hi:[1,1,1]
	v_pk_fma_f32 v[26:27], v[8:9], v[104:105], v[26:27] op_sel:[0,0,0] op_sel_hi:[0,1,1]
	v_pk_fma_f32 v[26:27], v[8:9], v[106:107], v[26:27] op_sel:[1,0,0] op_sel_hi:[1,1,1]
	v_pk_fma_f32 v[16:17], v[108:109], v[162:163], v[10:11] op_sel_hi:[1,0,1]
	v_pk_fma_f32 v[18:19], v[110:111], v[162:163], v[8:9] op_sel_hi:[1,0,1]
	v_add_f32_dpp v15, v26, v26 row_ror:8 row_mask:0xf bank_mask:0xf bound_ctrl:1
	ds_read_b128 v[92:95], v34 offset:9216
	s_nop 0
	v_add_f32_dpp v15, v15, v15 row_ror:4 row_mask:0xf bank_mask:0xf bound_ctrl:1
	ds_read_b128 v[80:83], v34 offset:8448
	ds_read_b128 v[84:87], v34 offset:8704
	v_add_f32_dpp v15, v15, v15 row_ror:2 row_mask:0xf bank_mask:0xf bound_ctrl:1
	ds_read_b128 v[88:91], v34 offset:8960
	ds_write2st64_b32 v37, v25, v27 offset0:16 offset1:20
	v_add_f32_dpp v30, v15, v15 row_ror:1 row_mask:0xf bank_mask:0xf bound_ctrl:1
	s_waitcnt lgkmcnt(5)
	v_pk_fma_f32 v[10:11], v[112:113], v[30:31], v[16:17] op_sel_hi:[1,0,1] neg_lo:[0,1,0] neg_hi:[0,1,0]
	v_pk_fma_f32 v[8:9], v[114:115], v[30:31], v[18:19] op_sel_hi:[1,0,1] neg_lo:[0,1,0] neg_hi:[0,1,0]
	v_pk_mul_f32 v[24:25], v[10:11], v[116:117] op_sel:[0,0] op_sel_hi:[0,1]
	v_pk_fma_f32 v[24:25], v[10:11], v[118:119], v[24:25] op_sel:[1,0,0] op_sel_hi:[1,1,1]
	v_pk_fma_f32 v[24:25], v[8:9], v[120:121], v[24:25] op_sel:[0,0,0] op_sel_hi:[0,1,1]
	v_pk_fma_f32 v[24:25], v[8:9], v[122:123], v[24:25] op_sel:[1,0,0] op_sel_hi:[1,1,1]
	v_pk_fma_f32 v[16:17], v[124:125], v[162:163], v[10:11] op_sel:[0,1,0] op_sel_hi:[1,1,1]
	v_pk_fma_f32 v[18:19], v[126:127], v[162:163], v[8:9] op_sel:[0,1,0] op_sel_hi:[1,1,1]
	v_add_f32_dpp v15, v24, v24 row_ror:8 row_mask:0xf bank_mask:0xf bound_ctrl:1
	ds_read_b128 v[108:111], v34 offset:10240
	s_nop 0
	v_add_f32_dpp v15, v15, v15 row_ror:4 row_mask:0xf bank_mask:0xf bound_ctrl:1
	ds_read_b128 v[96:99], v34 offset:9472
	ds_read_b128 v[100:103], v34 offset:9728
	v_add_f32_dpp v15, v15, v15 row_ror:2 row_mask:0xf bank_mask:0xf bound_ctrl:1
	ds_read_b128 v[104:107], v34 offset:9984
	s_nop 0
	v_add_f32_dpp v30, v15, v15 row_ror:1 row_mask:0xf bank_mask:0xf bound_ctrl:1
	v_pk_fma_f32 v[10:11], v[128:129], v[30:31], v[16:17] op_sel_hi:[1,0,1] neg_lo:[0,1,0] neg_hi:[0,1,0]
	v_pk_fma_f32 v[8:9], v[130:131], v[30:31], v[18:19] op_sel_hi:[1,0,1] neg_lo:[0,1,0] neg_hi:[0,1,0]
	v_pk_mul_f32 v[26:27], v[10:11], v[132:133] op_sel:[0,0] op_sel_hi:[0,1]
	v_pk_fma_f32 v[26:27], v[10:11], v[134:135], v[26:27] op_sel:[1,0,0] op_sel_hi:[1,1,1]
	v_pk_fma_f32 v[26:27], v[8:9], v[136:137], v[26:27] op_sel:[0,0,0] op_sel_hi:[0,1,1]
	v_pk_fma_f32 v[26:27], v[8:9], v[138:139], v[26:27] op_sel:[1,0,0] op_sel_hi:[1,1,1]
	v_pk_fma_f32 v[16:17], v[76:77], v[156:157], v[10:11] op_sel_hi:[1,0,1]
	v_pk_fma_f32 v[18:19], v[78:79], v[156:157], v[8:9] op_sel_hi:[1,0,1]
	v_add_f32_dpp v15, v26, v26 row_ror:8 row_mask:0xf bank_mask:0xf bound_ctrl:1
	ds_read_b128 v[124:127], v34 offset:11264
	s_nop 0
	v_add_f32_dpp v15, v15, v15 row_ror:4 row_mask:0xf bank_mask:0xf bound_ctrl:1
	ds_read_b128 v[112:115], v34 offset:10496
	ds_read_b128 v[116:119], v34 offset:10752
	v_add_f32_dpp v15, v15, v15 row_ror:2 row_mask:0xf bank_mask:0xf bound_ctrl:1
	ds_read_b128 v[120:123], v34 offset:11008
	ds_write2st64_b32 v37, v25, v27 offset0:24 offset1:28
	v_add_f32_dpp v30, v15, v15 row_ror:1 row_mask:0xf bank_mask:0xf bound_ctrl:1
	s_waitcnt lgkmcnt(5)
	v_pk_fma_f32 v[10:11], v[80:81], v[30:31], v[16:17] op_sel_hi:[1,0,1] neg_lo:[0,1,0] neg_hi:[0,1,0]
	v_pk_fma_f32 v[8:9], v[82:83], v[30:31], v[18:19] op_sel_hi:[1,0,1] neg_lo:[0,1,0] neg_hi:[0,1,0]
	v_pk_mul_f32 v[24:25], v[10:11], v[84:85] op_sel:[0,0] op_sel_hi:[0,1]
	v_pk_fma_f32 v[24:25], v[10:11], v[86:87], v[24:25] op_sel:[1,0,0] op_sel_hi:[1,1,1]
	v_pk_fma_f32 v[24:25], v[8:9], v[88:89], v[24:25] op_sel:[0,0,0] op_sel_hi:[0,1,1]
	v_pk_fma_f32 v[24:25], v[8:9], v[90:91], v[24:25] op_sel:[1,0,0] op_sel_hi:[1,1,1]
	v_pk_fma_f32 v[16:17], v[92:93], v[156:157], v[10:11] op_sel:[0,1,0] op_sel_hi:[1,1,1]
	v_pk_fma_f32 v[18:19], v[94:95], v[156:157], v[8:9] op_sel:[0,1,0] op_sel_hi:[1,1,1]
	v_add_f32_dpp v15, v24, v24 row_ror:8 row_mask:0xf bank_mask:0xf bound_ctrl:1
	ds_read_b128 v[76:79], v34 offset:12288
	s_nop 0
	v_add_f32_dpp v15, v15, v15 row_ror:4 row_mask:0xf bank_mask:0xf bound_ctrl:1
	ds_read_b128 v[128:131], v34 offset:11520
	ds_read_b128 v[132:135], v34 offset:11776
	v_add_f32_dpp v15, v15, v15 row_ror:2 row_mask:0xf bank_mask:0xf bound_ctrl:1
	ds_read_b128 v[136:139], v34 offset:12032
	ds_read_b128 v[160:163], v35 offset:48
	v_add_f32_dpp v30, v15, v15 row_ror:1 row_mask:0xf bank_mask:0xf bound_ctrl:1
	v_pk_fma_f32 v[10:11], v[96:97], v[30:31], v[16:17] op_sel_hi:[1,0,1] neg_lo:[0,1,0] neg_hi:[0,1,0]
	v_pk_fma_f32 v[8:9], v[98:99], v[30:31], v[18:19] op_sel_hi:[1,0,1] neg_lo:[0,1,0] neg_hi:[0,1,0]
	v_pk_mul_f32 v[26:27], v[10:11], v[100:101] op_sel:[0,0] op_sel_hi:[0,1]
	v_pk_fma_f32 v[26:27], v[10:11], v[102:103], v[26:27] op_sel:[1,0,0] op_sel_hi:[1,1,1]
	v_pk_fma_f32 v[26:27], v[8:9], v[104:105], v[26:27] op_sel:[0,0,0] op_sel_hi:[0,1,1]
	v_pk_fma_f32 v[26:27], v[8:9], v[106:107], v[26:27] op_sel:[1,0,0] op_sel_hi:[1,1,1]
	v_pk_fma_f32 v[16:17], v[108:109], v[158:159], v[10:11] op_sel_hi:[1,0,1]
	v_pk_fma_f32 v[18:19], v[110:111], v[158:159], v[8:9] op_sel_hi:[1,0,1]
	v_add_f32_dpp v15, v26, v26 row_ror:8 row_mask:0xf bank_mask:0xf bound_ctrl:1
	ds_read_b128 v[92:95], v34 offset:13312
	s_nop 0
	v_add_f32_dpp v15, v15, v15 row_ror:4 row_mask:0xf bank_mask:0xf bound_ctrl:1
	ds_read_b128 v[80:83], v34 offset:12544
	ds_read_b128 v[84:87], v34 offset:12800
	v_add_f32_dpp v15, v15, v15 row_ror:2 row_mask:0xf bank_mask:0xf bound_ctrl:1
	ds_read_b128 v[88:91], v34 offset:13056
	ds_write2st64_b32 v37, v25, v27 offset0:32 offset1:36
	v_add_f32_dpp v30, v15, v15 row_ror:1 row_mask:0xf bank_mask:0xf bound_ctrl:1
	s_waitcnt lgkmcnt(5)
	v_pk_fma_f32 v[10:11], v[112:113], v[30:31], v[16:17] op_sel_hi:[1,0,1] neg_lo:[0,1,0] neg_hi:[0,1,0]
	v_pk_fma_f32 v[8:9], v[114:115], v[30:31], v[18:19] op_sel_hi:[1,0,1] neg_lo:[0,1,0] neg_hi:[0,1,0]
	v_pk_mul_f32 v[24:25], v[10:11], v[116:117] op_sel:[0,0] op_sel_hi:[0,1]
	v_pk_fma_f32 v[24:25], v[10:11], v[118:119], v[24:25] op_sel:[1,0,0] op_sel_hi:[1,1,1]
	v_pk_fma_f32 v[24:25], v[8:9], v[120:121], v[24:25] op_sel:[0,0,0] op_sel_hi:[0,1,1]
	v_pk_fma_f32 v[24:25], v[8:9], v[122:123], v[24:25] op_sel:[1,0,0] op_sel_hi:[1,1,1]
	v_pk_fma_f32 v[16:17], v[124:125], v[158:159], v[10:11] op_sel:[0,1,0] op_sel_hi:[1,1,1]
	v_pk_fma_f32 v[18:19], v[126:127], v[158:159], v[8:9] op_sel:[0,1,0] op_sel_hi:[1,1,1]
	v_add_f32_dpp v15, v24, v24 row_ror:8 row_mask:0xf bank_mask:0xf bound_ctrl:1
	ds_read_b128 v[108:111], v34 offset:14336
	s_nop 0
	v_add_f32_dpp v15, v15, v15 row_ror:4 row_mask:0xf bank_mask:0xf bound_ctrl:1
	ds_read_b128 v[96:99], v34 offset:13568
	ds_read_b128 v[100:103], v34 offset:13824
	v_add_f32_dpp v15, v15, v15 row_ror:2 row_mask:0xf bank_mask:0xf bound_ctrl:1
	ds_read_b128 v[104:107], v34 offset:14080
	s_nop 0
	v_add_f32_dpp v30, v15, v15 row_ror:1 row_mask:0xf bank_mask:0xf bound_ctrl:1
	v_pk_fma_f32 v[10:11], v[128:129], v[30:31], v[16:17] op_sel_hi:[1,0,1] neg_lo:[0,1,0] neg_hi:[0,1,0]
	v_pk_fma_f32 v[8:9], v[130:131], v[30:31], v[18:19] op_sel_hi:[1,0,1] neg_lo:[0,1,0] neg_hi:[0,1,0]
	v_pk_mul_f32 v[26:27], v[10:11], v[132:133] op_sel:[0,0] op_sel_hi:[0,1]
	v_pk_fma_f32 v[26:27], v[10:11], v[134:135], v[26:27] op_sel:[1,0,0] op_sel_hi:[1,1,1]
	v_pk_fma_f32 v[26:27], v[8:9], v[136:137], v[26:27] op_sel:[0,0,0] op_sel_hi:[0,1,1]
	v_pk_fma_f32 v[26:27], v[8:9], v[138:139], v[26:27] op_sel:[1,0,0] op_sel_hi:[1,1,1]
	v_pk_fma_f32 v[16:17], v[76:77], v[160:161], v[10:11] op_sel_hi:[1,0,1]
	v_pk_fma_f32 v[18:19], v[78:79], v[160:161], v[8:9] op_sel_hi:[1,0,1]
	v_add_f32_dpp v15, v26, v26 row_ror:8 row_mask:0xf bank_mask:0xf bound_ctrl:1
	ds_read_b128 v[124:127], v34 offset:15360
	s_nop 0
	v_add_f32_dpp v15, v15, v15 row_ror:4 row_mask:0xf bank_mask:0xf bound_ctrl:1
	ds_read_b128 v[112:115], v34 offset:14592
	ds_read_b128 v[116:119], v34 offset:14848
	v_add_f32_dpp v15, v15, v15 row_ror:2 row_mask:0xf bank_mask:0xf bound_ctrl:1
	ds_read_b128 v[120:123], v34 offset:15104
	ds_write2st64_b32 v37, v25, v27 offset0:40 offset1:44
	v_add_f32_dpp v30, v15, v15 row_ror:1 row_mask:0xf bank_mask:0xf bound_ctrl:1
	s_waitcnt lgkmcnt(5)
	v_pk_fma_f32 v[10:11], v[80:81], v[30:31], v[16:17] op_sel_hi:[1,0,1] neg_lo:[0,1,0] neg_hi:[0,1,0]
	v_pk_fma_f32 v[8:9], v[82:83], v[30:31], v[18:19] op_sel_hi:[1,0,1] neg_lo:[0,1,0] neg_hi:[0,1,0]
	v_pk_mul_f32 v[24:25], v[10:11], v[84:85] op_sel:[0,0] op_sel_hi:[0,1]
	v_pk_fma_f32 v[24:25], v[10:11], v[86:87], v[24:25] op_sel:[1,0,0] op_sel_hi:[1,1,1]
	v_pk_fma_f32 v[24:25], v[8:9], v[88:89], v[24:25] op_sel:[0,0,0] op_sel_hi:[0,1,1]
	v_pk_fma_f32 v[24:25], v[8:9], v[90:91], v[24:25] op_sel:[1,0,0] op_sel_hi:[1,1,1]
	v_pk_fma_f32 v[16:17], v[92:93], v[160:161], v[10:11] op_sel:[0,1,0] op_sel_hi:[1,1,1]
	v_pk_fma_f32 v[18:19], v[94:95], v[160:161], v[8:9] op_sel:[0,1,0] op_sel_hi:[1,1,1]
	v_add_f32_dpp v15, v24, v24 row_ror:8 row_mask:0xf bank_mask:0xf bound_ctrl:1
	ds_read_b128 v[76:79], v34 offset:16384
	s_nop 0
	v_add_f32_dpp v15, v15, v15 row_ror:4 row_mask:0xf bank_mask:0xf bound_ctrl:1
	ds_read_b128 v[128:131], v34 offset:15616
	ds_read_b128 v[132:135], v34 offset:15872
	v_add_f32_dpp v15, v15, v15 row_ror:2 row_mask:0xf bank_mask:0xf bound_ctrl:1
	ds_read_b128 v[136:139], v34 offset:16128
	ds_read_b128 v[156:159], v35 offset:64
	v_add_f32_dpp v30, v15, v15 row_ror:1 row_mask:0xf bank_mask:0xf bound_ctrl:1
	v_pk_fma_f32 v[10:11], v[96:97], v[30:31], v[16:17] op_sel_hi:[1,0,1] neg_lo:[0,1,0] neg_hi:[0,1,0]
	v_pk_fma_f32 v[8:9], v[98:99], v[30:31], v[18:19] op_sel_hi:[1,0,1] neg_lo:[0,1,0] neg_hi:[0,1,0]
	v_pk_mul_f32 v[26:27], v[10:11], v[100:101] op_sel:[0,0] op_sel_hi:[0,1]
	v_pk_fma_f32 v[26:27], v[10:11], v[102:103], v[26:27] op_sel:[1,0,0] op_sel_hi:[1,1,1]
	v_pk_fma_f32 v[26:27], v[8:9], v[104:105], v[26:27] op_sel:[0,0,0] op_sel_hi:[0,1,1]
	v_pk_fma_f32 v[26:27], v[8:9], v[106:107], v[26:27] op_sel:[1,0,0] op_sel_hi:[1,1,1]
	v_pk_fma_f32 v[16:17], v[108:109], v[162:163], v[10:11] op_sel_hi:[1,0,1]
	v_pk_fma_f32 v[18:19], v[110:111], v[162:163], v[8:9] op_sel_hi:[1,0,1]
	v_add_f32_dpp v15, v26, v26 row_ror:8 row_mask:0xf bank_mask:0xf bound_ctrl:1
	ds_read_b128 v[92:95], v34 offset:17408
	s_nop 0
	v_add_f32_dpp v15, v15, v15 row_ror:4 row_mask:0xf bank_mask:0xf bound_ctrl:1
	ds_read_b128 v[80:83], v34 offset:16640
	ds_read_b128 v[84:87], v34 offset:16896
	v_add_f32_dpp v15, v15, v15 row_ror:2 row_mask:0xf bank_mask:0xf bound_ctrl:1
	ds_read_b128 v[88:91], v34 offset:17152
	ds_write2st64_b32 v37, v25, v27 offset0:48 offset1:52
	v_add_f32_dpp v30, v15, v15 row_ror:1 row_mask:0xf bank_mask:0xf bound_ctrl:1
	s_waitcnt lgkmcnt(5)
	v_pk_fma_f32 v[10:11], v[112:113], v[30:31], v[16:17] op_sel_hi:[1,0,1] neg_lo:[0,1,0] neg_hi:[0,1,0]
	v_pk_fma_f32 v[8:9], v[114:115], v[30:31], v[18:19] op_sel_hi:[1,0,1] neg_lo:[0,1,0] neg_hi:[0,1,0]
	v_pk_mul_f32 v[24:25], v[10:11], v[116:117] op_sel:[0,0] op_sel_hi:[0,1]
	v_pk_fma_f32 v[24:25], v[10:11], v[118:119], v[24:25] op_sel:[1,0,0] op_sel_hi:[1,1,1]
	v_pk_fma_f32 v[24:25], v[8:9], v[120:121], v[24:25] op_sel:[0,0,0] op_sel_hi:[0,1,1]
	v_pk_fma_f32 v[24:25], v[8:9], v[122:123], v[24:25] op_sel:[1,0,0] op_sel_hi:[1,1,1]
	v_pk_fma_f32 v[16:17], v[124:125], v[162:163], v[10:11] op_sel:[0,1,0] op_sel_hi:[1,1,1]
	v_pk_fma_f32 v[18:19], v[126:127], v[162:163], v[8:9] op_sel:[0,1,0] op_sel_hi:[1,1,1]
	v_add_f32_dpp v15, v24, v24 row_ror:8 row_mask:0xf bank_mask:0xf bound_ctrl:1
	ds_read_b128 v[108:111], v34 offset:18432
	s_nop 0
	v_add_f32_dpp v15, v15, v15 row_ror:4 row_mask:0xf bank_mask:0xf bound_ctrl:1
	ds_read_b128 v[96:99], v34 offset:17664
	ds_read_b128 v[100:103], v34 offset:17920
	v_add_f32_dpp v15, v15, v15 row_ror:2 row_mask:0xf bank_mask:0xf bound_ctrl:1
	ds_read_b128 v[104:107], v34 offset:18176
	s_nop 0
	v_add_f32_dpp v30, v15, v15 row_ror:1 row_mask:0xf bank_mask:0xf bound_ctrl:1
	v_pk_fma_f32 v[10:11], v[128:129], v[30:31], v[16:17] op_sel_hi:[1,0,1] neg_lo:[0,1,0] neg_hi:[0,1,0]
	v_pk_fma_f32 v[8:9], v[130:131], v[30:31], v[18:19] op_sel_hi:[1,0,1] neg_lo:[0,1,0] neg_hi:[0,1,0]
	v_pk_mul_f32 v[26:27], v[10:11], v[132:133] op_sel:[0,0] op_sel_hi:[0,1]
	v_pk_fma_f32 v[26:27], v[10:11], v[134:135], v[26:27] op_sel:[1,0,0] op_sel_hi:[1,1,1]
	v_pk_fma_f32 v[26:27], v[8:9], v[136:137], v[26:27] op_sel:[0,0,0] op_sel_hi:[0,1,1]
	v_pk_fma_f32 v[26:27], v[8:9], v[138:139], v[26:27] op_sel:[1,0,0] op_sel_hi:[1,1,1]
	v_pk_fma_f32 v[16:17], v[76:77], v[156:157], v[10:11] op_sel_hi:[1,0,1]
	v_pk_fma_f32 v[18:19], v[78:79], v[156:157], v[8:9] op_sel_hi:[1,0,1]
	v_add_f32_dpp v15, v26, v26 row_ror:8 row_mask:0xf bank_mask:0xf bound_ctrl:1
	ds_read_b128 v[124:127], v34 offset:19456
	s_nop 0
	v_add_f32_dpp v15, v15, v15 row_ror:4 row_mask:0xf bank_mask:0xf bound_ctrl:1
	ds_read_b128 v[112:115], v34 offset:18688
	ds_read_b128 v[116:119], v34 offset:18944
	v_add_f32_dpp v15, v15, v15 row_ror:2 row_mask:0xf bank_mask:0xf bound_ctrl:1
	ds_read_b128 v[120:123], v34 offset:19200
	ds_write2st64_b32 v37, v25, v27 offset0:56 offset1:60
	v_add_f32_dpp v30, v15, v15 row_ror:1 row_mask:0xf bank_mask:0xf bound_ctrl:1
	s_waitcnt lgkmcnt(5)
	v_pk_fma_f32 v[10:11], v[80:81], v[30:31], v[16:17] op_sel_hi:[1,0,1] neg_lo:[0,1,0] neg_hi:[0,1,0]
	v_pk_fma_f32 v[8:9], v[82:83], v[30:31], v[18:19] op_sel_hi:[1,0,1] neg_lo:[0,1,0] neg_hi:[0,1,0]
	v_pk_mul_f32 v[24:25], v[10:11], v[84:85] op_sel:[0,0] op_sel_hi:[0,1]
	v_pk_fma_f32 v[24:25], v[10:11], v[86:87], v[24:25] op_sel:[1,0,0] op_sel_hi:[1,1,1]
	v_pk_fma_f32 v[24:25], v[8:9], v[88:89], v[24:25] op_sel:[0,0,0] op_sel_hi:[0,1,1]
	v_pk_fma_f32 v[24:25], v[8:9], v[90:91], v[24:25] op_sel:[1,0,0] op_sel_hi:[1,1,1]
	v_pk_fma_f32 v[16:17], v[92:93], v[156:157], v[10:11] op_sel:[0,1,0] op_sel_hi:[1,1,1]
	v_pk_fma_f32 v[18:19], v[94:95], v[156:157], v[8:9] op_sel:[0,1,0] op_sel_hi:[1,1,1]
	v_add_f32_dpp v15, v24, v24 row_ror:8 row_mask:0xf bank_mask:0xf bound_ctrl:1
	ds_read_b128 v[76:79], v34 offset:20480
	s_nop 0
	v_add_f32_dpp v15, v15, v15 row_ror:4 row_mask:0xf bank_mask:0xf bound_ctrl:1
	ds_read_b128 v[128:131], v34 offset:19712
	ds_read_b128 v[132:135], v34 offset:19968
	v_add_f32_dpp v15, v15, v15 row_ror:2 row_mask:0xf bank_mask:0xf bound_ctrl:1
	ds_read_b128 v[136:139], v34 offset:20224
	ds_read_b128 v[160:163], v35 offset:80
	v_add_f32_dpp v30, v15, v15 row_ror:1 row_mask:0xf bank_mask:0xf bound_ctrl:1
	v_pk_fma_f32 v[10:11], v[96:97], v[30:31], v[16:17] op_sel_hi:[1,0,1] neg_lo:[0,1,0] neg_hi:[0,1,0]
	v_pk_fma_f32 v[8:9], v[98:99], v[30:31], v[18:19] op_sel_hi:[1,0,1] neg_lo:[0,1,0] neg_hi:[0,1,0]
	v_pk_mul_f32 v[26:27], v[10:11], v[100:101] op_sel:[0,0] op_sel_hi:[0,1]
	v_pk_fma_f32 v[26:27], v[10:11], v[102:103], v[26:27] op_sel:[1,0,0] op_sel_hi:[1,1,1]
	v_pk_fma_f32 v[26:27], v[8:9], v[104:105], v[26:27] op_sel:[0,0,0] op_sel_hi:[0,1,1]
	v_pk_fma_f32 v[26:27], v[8:9], v[106:107], v[26:27] op_sel:[1,0,0] op_sel_hi:[1,1,1]
	v_pk_fma_f32 v[16:17], v[108:109], v[158:159], v[10:11] op_sel_hi:[1,0,1]
	v_pk_fma_f32 v[18:19], v[110:111], v[158:159], v[8:9] op_sel_hi:[1,0,1]
	v_add_f32_dpp v15, v26, v26 row_ror:8 row_mask:0xf bank_mask:0xf bound_ctrl:1
	ds_read_b128 v[92:95], v34 offset:21504
	s_nop 0
	v_add_f32_dpp v15, v15, v15 row_ror:4 row_mask:0xf bank_mask:0xf bound_ctrl:1
	ds_read_b128 v[80:83], v34 offset:20736
	ds_read_b128 v[84:87], v34 offset:20992
	v_add_f32_dpp v15, v15, v15 row_ror:2 row_mask:0xf bank_mask:0xf bound_ctrl:1
	ds_read_b128 v[88:91], v34 offset:21248
	ds_write2st64_b32 v37, v25, v27 offset0:64 offset1:68
	v_add_f32_dpp v30, v15, v15 row_ror:1 row_mask:0xf bank_mask:0xf bound_ctrl:1
	s_waitcnt lgkmcnt(5)
	v_pk_fma_f32 v[10:11], v[112:113], v[30:31], v[16:17] op_sel_hi:[1,0,1] neg_lo:[0,1,0] neg_hi:[0,1,0]
	v_pk_fma_f32 v[8:9], v[114:115], v[30:31], v[18:19] op_sel_hi:[1,0,1] neg_lo:[0,1,0] neg_hi:[0,1,0]
	v_pk_mul_f32 v[24:25], v[10:11], v[116:117] op_sel:[0,0] op_sel_hi:[0,1]
	v_pk_fma_f32 v[24:25], v[10:11], v[118:119], v[24:25] op_sel:[1,0,0] op_sel_hi:[1,1,1]
	v_pk_fma_f32 v[24:25], v[8:9], v[120:121], v[24:25] op_sel:[0,0,0] op_sel_hi:[0,1,1]
	v_pk_fma_f32 v[24:25], v[8:9], v[122:123], v[24:25] op_sel:[1,0,0] op_sel_hi:[1,1,1]
	v_pk_fma_f32 v[16:17], v[124:125], v[158:159], v[10:11] op_sel:[0,1,0] op_sel_hi:[1,1,1]
	v_pk_fma_f32 v[18:19], v[126:127], v[158:159], v[8:9] op_sel:[0,1,0] op_sel_hi:[1,1,1]
	v_add_f32_dpp v15, v24, v24 row_ror:8 row_mask:0xf bank_mask:0xf bound_ctrl:1
	ds_read_b128 v[108:111], v34 offset:22528
	s_nop 0
	v_add_f32_dpp v15, v15, v15 row_ror:4 row_mask:0xf bank_mask:0xf bound_ctrl:1
	ds_read_b128 v[96:99], v34 offset:21760
	ds_read_b128 v[100:103], v34 offset:22016
	v_add_f32_dpp v15, v15, v15 row_ror:2 row_mask:0xf bank_mask:0xf bound_ctrl:1
	ds_read_b128 v[104:107], v34 offset:22272
	s_nop 0
	v_add_f32_dpp v30, v15, v15 row_ror:1 row_mask:0xf bank_mask:0xf bound_ctrl:1
	v_pk_fma_f32 v[10:11], v[128:129], v[30:31], v[16:17] op_sel_hi:[1,0,1] neg_lo:[0,1,0] neg_hi:[0,1,0]
	v_pk_fma_f32 v[8:9], v[130:131], v[30:31], v[18:19] op_sel_hi:[1,0,1] neg_lo:[0,1,0] neg_hi:[0,1,0]
	v_pk_mul_f32 v[26:27], v[10:11], v[132:133] op_sel:[0,0] op_sel_hi:[0,1]
	v_pk_fma_f32 v[26:27], v[10:11], v[134:135], v[26:27] op_sel:[1,0,0] op_sel_hi:[1,1,1]
	v_pk_fma_f32 v[26:27], v[8:9], v[136:137], v[26:27] op_sel:[0,0,0] op_sel_hi:[0,1,1]
	v_pk_fma_f32 v[26:27], v[8:9], v[138:139], v[26:27] op_sel:[1,0,0] op_sel_hi:[1,1,1]
	v_pk_fma_f32 v[16:17], v[76:77], v[160:161], v[10:11] op_sel_hi:[1,0,1]
	v_pk_fma_f32 v[18:19], v[78:79], v[160:161], v[8:9] op_sel_hi:[1,0,1]
	v_add_f32_dpp v15, v26, v26 row_ror:8 row_mask:0xf bank_mask:0xf bound_ctrl:1
	ds_read_b128 v[124:127], v34 offset:23552
	s_nop 0
	v_add_f32_dpp v15, v15, v15 row_ror:4 row_mask:0xf bank_mask:0xf bound_ctrl:1
	ds_read_b128 v[112:115], v34 offset:22784
	ds_read_b128 v[116:119], v34 offset:23040
	v_add_f32_dpp v15, v15, v15 row_ror:2 row_mask:0xf bank_mask:0xf bound_ctrl:1
	ds_read_b128 v[120:123], v34 offset:23296
	ds_write2st64_b32 v37, v25, v27 offset0:72 offset1:76
	v_add_f32_dpp v30, v15, v15 row_ror:1 row_mask:0xf bank_mask:0xf bound_ctrl:1
	s_waitcnt lgkmcnt(5)
	v_pk_fma_f32 v[10:11], v[80:81], v[30:31], v[16:17] op_sel_hi:[1,0,1] neg_lo:[0,1,0] neg_hi:[0,1,0]
	v_pk_fma_f32 v[8:9], v[82:83], v[30:31], v[18:19] op_sel_hi:[1,0,1] neg_lo:[0,1,0] neg_hi:[0,1,0]
	v_pk_mul_f32 v[24:25], v[10:11], v[84:85] op_sel:[0,0] op_sel_hi:[0,1]
	v_pk_fma_f32 v[24:25], v[10:11], v[86:87], v[24:25] op_sel:[1,0,0] op_sel_hi:[1,1,1]
	v_pk_fma_f32 v[24:25], v[8:9], v[88:89], v[24:25] op_sel:[0,0,0] op_sel_hi:[0,1,1]
	v_pk_fma_f32 v[24:25], v[8:9], v[90:91], v[24:25] op_sel:[1,0,0] op_sel_hi:[1,1,1]
	v_pk_fma_f32 v[16:17], v[92:93], v[160:161], v[10:11] op_sel:[0,1,0] op_sel_hi:[1,1,1]
	v_pk_fma_f32 v[18:19], v[94:95], v[160:161], v[8:9] op_sel:[0,1,0] op_sel_hi:[1,1,1]
	v_add_f32_dpp v15, v24, v24 row_ror:8 row_mask:0xf bank_mask:0xf bound_ctrl:1
	ds_read_b128 v[76:79], v34 offset:24576
	s_nop 0
	v_add_f32_dpp v15, v15, v15 row_ror:4 row_mask:0xf bank_mask:0xf bound_ctrl:1
	ds_read_b128 v[128:131], v34 offset:23808
	ds_read_b128 v[132:135], v34 offset:24064
	v_add_f32_dpp v15, v15, v15 row_ror:2 row_mask:0xf bank_mask:0xf bound_ctrl:1
	ds_read_b128 v[136:139], v34 offset:24320
	ds_read_b128 v[156:159], v35 offset:96
	v_add_f32_dpp v30, v15, v15 row_ror:1 row_mask:0xf bank_mask:0xf bound_ctrl:1
	v_pk_fma_f32 v[10:11], v[96:97], v[30:31], v[16:17] op_sel_hi:[1,0,1] neg_lo:[0,1,0] neg_hi:[0,1,0]
	v_pk_fma_f32 v[8:9], v[98:99], v[30:31], v[18:19] op_sel_hi:[1,0,1] neg_lo:[0,1,0] neg_hi:[0,1,0]
	v_pk_mul_f32 v[26:27], v[10:11], v[100:101] op_sel:[0,0] op_sel_hi:[0,1]
	v_pk_fma_f32 v[26:27], v[10:11], v[102:103], v[26:27] op_sel:[1,0,0] op_sel_hi:[1,1,1]
	v_pk_fma_f32 v[26:27], v[8:9], v[104:105], v[26:27] op_sel:[0,0,0] op_sel_hi:[0,1,1]
	v_pk_fma_f32 v[26:27], v[8:9], v[106:107], v[26:27] op_sel:[1,0,0] op_sel_hi:[1,1,1]
	v_pk_fma_f32 v[16:17], v[108:109], v[162:163], v[10:11] op_sel_hi:[1,0,1]
	v_pk_fma_f32 v[18:19], v[110:111], v[162:163], v[8:9] op_sel_hi:[1,0,1]
	v_add_f32_dpp v15, v26, v26 row_ror:8 row_mask:0xf bank_mask:0xf bound_ctrl:1
	ds_read_b128 v[92:95], v34 offset:25600
	s_nop 0
	v_add_f32_dpp v15, v15, v15 row_ror:4 row_mask:0xf bank_mask:0xf bound_ctrl:1
	ds_read_b128 v[80:83], v34 offset:24832
	ds_read_b128 v[84:87], v34 offset:25088
	v_add_f32_dpp v15, v15, v15 row_ror:2 row_mask:0xf bank_mask:0xf bound_ctrl:1
	ds_read_b128 v[88:91], v34 offset:25344
	ds_write2st64_b32 v37, v25, v27 offset0:80 offset1:84
	v_add_f32_dpp v30, v15, v15 row_ror:1 row_mask:0xf bank_mask:0xf bound_ctrl:1
	s_waitcnt lgkmcnt(5)
	v_pk_fma_f32 v[10:11], v[112:113], v[30:31], v[16:17] op_sel_hi:[1,0,1] neg_lo:[0,1,0] neg_hi:[0,1,0]
	v_pk_fma_f32 v[8:9], v[114:115], v[30:31], v[18:19] op_sel_hi:[1,0,1] neg_lo:[0,1,0] neg_hi:[0,1,0]
	v_pk_mul_f32 v[24:25], v[10:11], v[116:117] op_sel:[0,0] op_sel_hi:[0,1]
	v_pk_fma_f32 v[24:25], v[10:11], v[118:119], v[24:25] op_sel:[1,0,0] op_sel_hi:[1,1,1]
	v_pk_fma_f32 v[24:25], v[8:9], v[120:121], v[24:25] op_sel:[0,0,0] op_sel_hi:[0,1,1]
	v_pk_fma_f32 v[24:25], v[8:9], v[122:123], v[24:25] op_sel:[1,0,0] op_sel_hi:[1,1,1]
	v_pk_fma_f32 v[16:17], v[124:125], v[162:163], v[10:11] op_sel:[0,1,0] op_sel_hi:[1,1,1]
	v_pk_fma_f32 v[18:19], v[126:127], v[162:163], v[8:9] op_sel:[0,1,0] op_sel_hi:[1,1,1]
	v_add_f32_dpp v15, v24, v24 row_ror:8 row_mask:0xf bank_mask:0xf bound_ctrl:1
	ds_read_b128 v[108:111], v34 offset:26624
	s_nop 0
	v_add_f32_dpp v15, v15, v15 row_ror:4 row_mask:0xf bank_mask:0xf bound_ctrl:1
	ds_read_b128 v[96:99], v34 offset:25856
	ds_read_b128 v[100:103], v34 offset:26112
	v_add_f32_dpp v15, v15, v15 row_ror:2 row_mask:0xf bank_mask:0xf bound_ctrl:1
	ds_read_b128 v[104:107], v34 offset:26368
	s_nop 0
	v_add_f32_dpp v30, v15, v15 row_ror:1 row_mask:0xf bank_mask:0xf bound_ctrl:1
	v_pk_fma_f32 v[10:11], v[128:129], v[30:31], v[16:17] op_sel_hi:[1,0,1] neg_lo:[0,1,0] neg_hi:[0,1,0]
	v_pk_fma_f32 v[8:9], v[130:131], v[30:31], v[18:19] op_sel_hi:[1,0,1] neg_lo:[0,1,0] neg_hi:[0,1,0]
	v_pk_mul_f32 v[26:27], v[10:11], v[132:133] op_sel:[0,0] op_sel_hi:[0,1]
	v_pk_fma_f32 v[26:27], v[10:11], v[134:135], v[26:27] op_sel:[1,0,0] op_sel_hi:[1,1,1]
	v_pk_fma_f32 v[26:27], v[8:9], v[136:137], v[26:27] op_sel:[0,0,0] op_sel_hi:[0,1,1]
	v_pk_fma_f32 v[26:27], v[8:9], v[138:139], v[26:27] op_sel:[1,0,0] op_sel_hi:[1,1,1]
	v_pk_fma_f32 v[16:17], v[76:77], v[156:157], v[10:11] op_sel_hi:[1,0,1]
	v_pk_fma_f32 v[18:19], v[78:79], v[156:157], v[8:9] op_sel_hi:[1,0,1]
	v_add_f32_dpp v15, v26, v26 row_ror:8 row_mask:0xf bank_mask:0xf bound_ctrl:1
	ds_read_b128 v[124:127], v34 offset:27648
	s_nop 0
	v_add_f32_dpp v15, v15, v15 row_ror:4 row_mask:0xf bank_mask:0xf bound_ctrl:1
	ds_read_b128 v[112:115], v34 offset:26880
	ds_read_b128 v[116:119], v34 offset:27136
	v_add_f32_dpp v15, v15, v15 row_ror:2 row_mask:0xf bank_mask:0xf bound_ctrl:1
	ds_read_b128 v[120:123], v34 offset:27392
	ds_write2st64_b32 v37, v25, v27 offset0:88 offset1:92
	v_add_f32_dpp v30, v15, v15 row_ror:1 row_mask:0xf bank_mask:0xf bound_ctrl:1
	s_waitcnt lgkmcnt(5)
	v_pk_fma_f32 v[10:11], v[80:81], v[30:31], v[16:17] op_sel_hi:[1,0,1] neg_lo:[0,1,0] neg_hi:[0,1,0]
	v_pk_fma_f32 v[8:9], v[82:83], v[30:31], v[18:19] op_sel_hi:[1,0,1] neg_lo:[0,1,0] neg_hi:[0,1,0]
	v_pk_mul_f32 v[24:25], v[10:11], v[84:85] op_sel:[0,0] op_sel_hi:[0,1]
	v_pk_fma_f32 v[24:25], v[10:11], v[86:87], v[24:25] op_sel:[1,0,0] op_sel_hi:[1,1,1]
	v_pk_fma_f32 v[24:25], v[8:9], v[88:89], v[24:25] op_sel:[0,0,0] op_sel_hi:[0,1,1]
	v_pk_fma_f32 v[24:25], v[8:9], v[90:91], v[24:25] op_sel:[1,0,0] op_sel_hi:[1,1,1]
	v_pk_fma_f32 v[16:17], v[92:93], v[156:157], v[10:11] op_sel:[0,1,0] op_sel_hi:[1,1,1]
	v_pk_fma_f32 v[18:19], v[94:95], v[156:157], v[8:9] op_sel:[0,1,0] op_sel_hi:[1,1,1]
	v_add_f32_dpp v15, v24, v24 row_ror:8 row_mask:0xf bank_mask:0xf bound_ctrl:1
	ds_read_b128 v[76:79], v34 offset:28672
	s_nop 0
	v_add_f32_dpp v15, v15, v15 row_ror:4 row_mask:0xf bank_mask:0xf bound_ctrl:1
	ds_read_b128 v[128:131], v34 offset:27904
	ds_read_b128 v[132:135], v34 offset:28160
	v_add_f32_dpp v15, v15, v15 row_ror:2 row_mask:0xf bank_mask:0xf bound_ctrl:1
	ds_read_b128 v[136:139], v34 offset:28416
	ds_read_b128 v[160:163], v35 offset:112
	v_add_f32_dpp v30, v15, v15 row_ror:1 row_mask:0xf bank_mask:0xf bound_ctrl:1
	ds_read_b128 v[56:59], v52
	v_pk_fma_f32 v[10:11], v[96:97], v[30:31], v[16:17] op_sel_hi:[1,0,1] neg_lo:[0,1,0] neg_hi:[0,1,0]
	v_pk_fma_f32 v[8:9], v[98:99], v[30:31], v[18:19] op_sel_hi:[1,0,1] neg_lo:[0,1,0] neg_hi:[0,1,0]
	v_pk_mul_f32 v[26:27], v[10:11], v[100:101] op_sel:[0,0] op_sel_hi:[0,1]
	v_pk_fma_f32 v[26:27], v[10:11], v[102:103], v[26:27] op_sel:[1,0,0] op_sel_hi:[1,1,1]
	v_pk_fma_f32 v[26:27], v[8:9], v[104:105], v[26:27] op_sel:[0,0,0] op_sel_hi:[0,1,1]
	v_pk_fma_f32 v[26:27], v[8:9], v[106:107], v[26:27] op_sel:[1,0,0] op_sel_hi:[1,1,1]
	v_pk_fma_f32 v[16:17], v[108:109], v[158:159], v[10:11] op_sel_hi:[1,0,1]
	v_pk_fma_f32 v[18:19], v[110:111], v[158:159], v[8:9] op_sel_hi:[1,0,1]
	v_add_f32_dpp v15, v26, v26 row_ror:8 row_mask:0xf bank_mask:0xf bound_ctrl:1
	ds_read_b128 v[92:95], v34 offset:29696
	s_nop 0
	v_add_f32_dpp v15, v15, v15 row_ror:4 row_mask:0xf bank_mask:0xf bound_ctrl:1
	ds_read_b128 v[80:83], v34 offset:28928
	ds_read_b128 v[84:87], v34 offset:29184
	v_add_f32_dpp v15, v15, v15 row_ror:2 row_mask:0xf bank_mask:0xf bound_ctrl:1
	ds_read_b128 v[88:91], v34 offset:29440
	ds_write2st64_b32 v37, v25, v27 offset0:96 offset1:100
	v_add_f32_dpp v30, v15, v15 row_ror:1 row_mask:0xf bank_mask:0xf bound_ctrl:1
	s_waitcnt lgkmcnt(5)
	v_min_u32_e32 v56, v56, v57
	v_min3_u32 v56, v56, v58, v59
	v_pk_fma_f32 v[10:11], v[112:113], v[30:31], v[16:17] op_sel_hi:[1,0,1] neg_lo:[0,1,0] neg_hi:[0,1,0]
	v_pk_fma_f32 v[8:9], v[114:115], v[30:31], v[18:19] op_sel_hi:[1,0,1] neg_lo:[0,1,0] neg_hi:[0,1,0]
	v_pk_mul_f32 v[24:25], v[10:11], v[116:117] op_sel:[0,0] op_sel_hi:[0,1]
	v_pk_fma_f32 v[24:25], v[10:11], v[118:119], v[24:25] op_sel:[1,0,0] op_sel_hi:[1,1,1]
	v_pk_fma_f32 v[24:25], v[8:9], v[120:121], v[24:25] op_sel:[0,0,0] op_sel_hi:[0,1,1]
	v_pk_fma_f32 v[24:25], v[8:9], v[122:123], v[24:25] op_sel:[1,0,0] op_sel_hi:[1,1,1]
	v_pk_fma_f32 v[16:17], v[124:125], v[158:159], v[10:11] op_sel:[0,1,0] op_sel_hi:[1,1,1]
	v_pk_fma_f32 v[18:19], v[126:127], v[158:159], v[8:9] op_sel:[0,1,0] op_sel_hi:[1,1,1]
	v_add_f32_dpp v15, v24, v24 row_ror:8 row_mask:0xf bank_mask:0xf bound_ctrl:1
	ds_read_b128 v[108:111], v34 offset:30720
	s_nop 0
	v_add_f32_dpp v15, v15, v15 row_ror:4 row_mask:0xf bank_mask:0xf bound_ctrl:1
	ds_read_b128 v[96:99], v34 offset:29952
	ds_read_b128 v[100:103], v34 offset:30208
	v_add_f32_dpp v15, v15, v15 row_ror:2 row_mask:0xf bank_mask:0xf bound_ctrl:1
	ds_read_b128 v[104:107], v34 offset:30464
	s_nop 0
	v_add_f32_dpp v30, v15, v15 row_ror:1 row_mask:0xf bank_mask:0xf bound_ctrl:1
	v_pk_fma_f32 v[10:11], v[128:129], v[30:31], v[16:17] op_sel_hi:[1,0,1] neg_lo:[0,1,0] neg_hi:[0,1,0]
	v_pk_fma_f32 v[8:9], v[130:131], v[30:31], v[18:19] op_sel_hi:[1,0,1] neg_lo:[0,1,0] neg_hi:[0,1,0]
	v_pk_mul_f32 v[26:27], v[10:11], v[132:133] op_sel:[0,0] op_sel_hi:[0,1]
	v_pk_fma_f32 v[26:27], v[10:11], v[134:135], v[26:27] op_sel:[1,0,0] op_sel_hi:[1,1,1]
	v_pk_fma_f32 v[26:27], v[8:9], v[136:137], v[26:27] op_sel:[0,0,0] op_sel_hi:[0,1,1]
	v_pk_fma_f32 v[26:27], v[8:9], v[138:139], v[26:27] op_sel:[1,0,0] op_sel_hi:[1,1,1]
	v_pk_fma_f32 v[16:17], v[76:77], v[160:161], v[10:11] op_sel_hi:[1,0,1]
	v_pk_fma_f32 v[18:19], v[78:79], v[160:161], v[8:9] op_sel_hi:[1,0,1]
	v_add_f32_dpp v15, v26, v26 row_ror:8 row_mask:0xf bank_mask:0xf bound_ctrl:1
	ds_read_b128 v[124:127], v34 offset:31744
	s_nop 0
	v_add_f32_dpp v15, v15, v15 row_ror:4 row_mask:0xf bank_mask:0xf bound_ctrl:1
	ds_read_b128 v[112:115], v34 offset:30976
	ds_read_b128 v[116:119], v34 offset:31232
	v_add_f32_dpp v15, v15, v15 row_ror:2 row_mask:0xf bank_mask:0xf bound_ctrl:1
	ds_read_b128 v[120:123], v34 offset:31488
	ds_read_b128 v[140:143], v34 offset:34560
	ds_write2st64_b32 v37, v25, v27 offset0:104 offset1:108
	v_add_f32_dpp v30, v15, v15 row_ror:1 row_mask:0xf bank_mask:0xf bound_ctrl:1
	v_readfirstlane_b32 s54, v56
	s_add_u32 s64, s6, 2
	s_cmp_lt_u32 s54, s64
	s_cbranch_scc1 .Lss_spin_0
.Lss_ok_0:
	s_waitcnt lgkmcnt(6)
	v_pk_fma_f32 v[10:11], v[80:81], v[30:31], v[16:17] op_sel_hi:[1,0,1] neg_lo:[0,1,0] neg_hi:[0,1,0]
	v_pk_fma_f32 v[8:9], v[82:83], v[30:31], v[18:19] op_sel_hi:[1,0,1] neg_lo:[0,1,0] neg_hi:[0,1,0]
	v_pk_mul_f32 v[24:25], v[10:11], v[84:85] op_sel:[0,0] op_sel_hi:[0,1]
	v_pk_fma_f32 v[24:25], v[10:11], v[86:87], v[24:25] op_sel:[1,0,0] op_sel_hi:[1,1,1]
	v_pk_fma_f32 v[24:25], v[8:9], v[88:89], v[24:25] op_sel:[0,0,0] op_sel_hi:[0,1,1]
	v_pk_fma_f32 v[24:25], v[8:9], v[90:91], v[24:25] op_sel:[1,0,0] op_sel_hi:[1,1,1]
	v_pk_fma_f32 v[16:17], v[92:93], v[160:161], v[10:11] op_sel:[0,1,0] op_sel_hi:[1,1,1]
	v_pk_fma_f32 v[18:19], v[94:95], v[160:161], v[8:9] op_sel:[0,1,0] op_sel_hi:[1,1,1]
	v_add_f32_dpp v15, v24, v24 row_ror:8 row_mask:0xf bank_mask:0xf bound_ctrl:1
	ds_read_b128 v[76:79], v48 offset:0
	s_nop 0
	v_add_f32_dpp v15, v15, v15 row_ror:4 row_mask:0xf bank_mask:0xf bound_ctrl:1
	ds_read_b128 v[128:131], v34 offset:32000
	ds_read_b128 v[132:135], v34 offset:32256
	v_add_f32_dpp v15, v15, v15 row_ror:2 row_mask:0xf bank_mask:0xf bound_ctrl:1
	ds_read_b128 v[136:139], v34 offset:32512
	s_nop 0
	v_add_f32_dpp v30, v15, v15 row_ror:1 row_mask:0xf bank_mask:0xf bound_ctrl:1
	v_pk_fma_f32 v[10:11], v[96:97], v[30:31], v[16:17] op_sel_hi:[1,0,1] neg_lo:[0,1,0] neg_hi:[0,1,0]
	v_pk_fma_f32 v[8:9], v[98:99], v[30:31], v[18:19] op_sel_hi:[1,0,1] neg_lo:[0,1,0] neg_hi:[0,1,0]
	v_pk_mul_f32 v[26:27], v[10:11], v[100:101] op_sel:[0,0] op_sel_hi:[0,1]
	v_pk_fma_f32 v[26:27], v[10:11], v[102:103], v[26:27] op_sel:[1,0,0] op_sel_hi:[1,1,1]
	v_pk_fma_f32 v[26:27], v[8:9], v[104:105], v[26:27] op_sel:[0,0,0] op_sel_hi:[0,1,1]
	v_pk_fma_f32 v[26:27], v[8:9], v[106:107], v[26:27] op_sel:[1,0,0] op_sel_hi:[1,1,1]
	v_pk_fma_f32 v[16:17], v[108:109], v[162:163], v[10:11] op_sel_hi:[1,0,1]
	v_pk_fma_f32 v[18:19], v[110:111], v[162:163], v[8:9] op_sel_hi:[1,0,1]
	v_add_f32_dpp v15, v26, v26 row_ror:8 row_mask:0xf bank_mask:0xf bound_ctrl:1
	ds_read_b128 v[92:95], v48 offset:1024
	s_nop 0
	v_add_f32_dpp v15, v15, v15 row_ror:4 row_mask:0xf bank_mask:0xf bound_ctrl:1
	ds_read_b128 v[80:83], v48 offset:256
	ds_read_b128 v[84:87], v48 offset:512
	v_add_f32_dpp v15, v15, v15 row_ror:2 row_mask:0xf bank_mask:0xf bound_ctrl:1
	ds_read_b128 v[88:91], v48 offset:768
	ds_read_b128 v[144:147], v48 offset:32768
	ds_write2st64_b32 v37, v25, v27 offset0:112 offset1:116
	v_add_f32_dpp v30, v15, v15 row_ror:1 row_mask:0xf bank_mask:0xf bound_ctrl:1
	ds_read_b128 v[156:159], v49 offset:0
	s_waitcnt lgkmcnt(7)
	v_pk_fma_f32 v[10:11], v[112:113], v[30:31], v[16:17] op_sel_hi:[1,0,1] neg_lo:[0,1,0] neg_hi:[0,1,0]
	v_pk_fma_f32 v[8:9], v[114:115], v[30:31], v[18:19] op_sel_hi:[1,0,1] neg_lo:[0,1,0] neg_hi:[0,1,0]
	v_pk_mul_f32 v[24:25], v[10:11], v[116:117] op_sel:[0,0] op_sel_hi:[0,1]
	v_pk_fma_f32 v[24:25], v[10:11], v[118:119], v[24:25] op_sel:[1,0,0] op_sel_hi:[1,1,1]
	v_pk_fma_f32 v[24:25], v[8:9], v[120:121], v[24:25] op_sel:[0,0,0] op_sel_hi:[0,1,1]
	v_pk_fma_f32 v[24:25], v[8:9], v[122:123], v[24:25] op_sel:[1,0,0] op_sel_hi:[1,1,1]
	v_pk_fma_f32 v[16:17], v[124:125], v[162:163], v[10:11] op_sel:[0,1,0] op_sel_hi:[1,1,1]
	v_pk_fma_f32 v[18:19], v[126:127], v[162:163], v[8:9] op_sel:[0,1,0] op_sel_hi:[1,1,1]
	v_add_f32_dpp v15, v24, v24 row_ror:8 row_mask:0xf bank_mask:0xf bound_ctrl:1
	ds_read_b128 v[108:111], v48 offset:2048
	s_nop 0
	v_add_f32_dpp v15, v15, v15 row_ror:4 row_mask:0xf bank_mask:0xf bound_ctrl:1
	ds_read_b128 v[96:99], v48 offset:1280
	ds_read_b128 v[100:103], v48 offset:1536
	v_add_f32_dpp v15, v15, v15 row_ror:2 row_mask:0xf bank_mask:0xf bound_ctrl:1
	ds_read_b128 v[104:107], v48 offset:1792
	s_nop 0
	v_add_f32_dpp v30, v15, v15 row_ror:1 row_mask:0xf bank_mask:0xf bound_ctrl:1
	v_pk_fma_f32 v[10:11], v[128:129], v[30:31], v[16:17] op_sel_hi:[1,0,1] neg_lo:[0,1,0] neg_hi:[0,1,0]
	v_pk_fma_f32 v[8:9], v[130:131], v[30:31], v[18:19] op_sel_hi:[1,0,1] neg_lo:[0,1,0] neg_hi:[0,1,0]
	v_pk_mul_f32 v[26:27], v[10:11], v[132:133] op_sel:[0,0] op_sel_hi:[0,1]
	v_pk_fma_f32 v[26:27], v[10:11], v[134:135], v[26:27] op_sel:[1,0,0] op_sel_hi:[1,1,1]
	v_pk_fma_f32 v[26:27], v[8:9], v[136:137], v[26:27] op_sel:[0,0,0] op_sel_hi:[0,1,1]
	v_pk_fma_f32 v[26:27], v[8:9], v[138:139], v[26:27] op_sel:[1,0,0] op_sel_hi:[1,1,1]
	ds_write2st64_b32 v37, v25, v27 offset0:120 offset1:124
	v_pk_mul_f32 v[10:11], v[10:11], v[140:141]
	v_pk_mul_f32 v[8:9], v[8:9], v[142:143]
	s_waitcnt lgkmcnt(7)
	v_pk_mul_f32 v[24:25], v[10:11], v[144:145]
	v_pk_fma_f32 v[24:25], v[8:9], v[146:147], v[24:25]
	v_add_f32_e32 v24, v24, v25
	s_waitcnt lgkmcnt(5)
	v_pk_fma_f32 v[16:17], v[76:77], v[156:157], v[10:11] op_sel_hi:[1,0,1]
	v_pk_fma_f32 v[18:19], v[78:79], v[156:157], v[8:9] op_sel_hi:[1,0,1]
	v_add_f32_dpp v15, v24, v24 row_ror:8 row_mask:0xf bank_mask:0xf bound_ctrl:1
	v_add_u32_e32 v51, 1, v51
	s_add_u32 s6, s6, 1
	v_add_f32_dpp v15, v15, v15 row_ror:4 row_mask:0xf bank_mask:0xf bound_ctrl:1
	ds_write_b32 v53, v51
	ds_read_b128 v[124:127], v48 offset:3072
	v_add_f32_dpp v15, v15, v15 row_ror:2 row_mask:0xf bank_mask:0xf bound_ctrl:1
	ds_read_b128 v[112:115], v48 offset:2304
	ds_read_b128 v[116:119], v48 offset:2560
	v_add_f32_dpp v30, v15, v15 row_ror:1 row_mask:0xf bank_mask:0xf bound_ctrl:1
	ds_read_b128 v[120:123], v48 offset:2816
	s_waitcnt lgkmcnt(4)
	v_pk_fma_f32 v[10:11], v[80:81], v[30:31], v[16:17] op_sel_hi:[1,0,1] neg_lo:[0,1,0] neg_hi:[0,1,0]
	v_pk_fma_f32 v[8:9], v[82:83], v[30:31], v[18:19] op_sel_hi:[1,0,1] neg_lo:[0,1,0] neg_hi:[0,1,0]
	v_pk_mul_f32 v[24:25], v[10:11], v[84:85] op_sel:[0,0] op_sel_hi:[0,1]
	v_pk_fma_f32 v[24:25], v[10:11], v[86:87], v[24:25] op_sel:[1,0,0] op_sel_hi:[1,1,1]
	v_pk_fma_f32 v[24:25], v[8:9], v[88:89], v[24:25] op_sel:[0,0,0] op_sel_hi:[0,1,1]
	v_pk_fma_f32 v[24:25], v[8:9], v[90:91], v[24:25] op_sel:[1,0,0] op_sel_hi:[1,1,1]
	v_pk_fma_f32 v[16:17], v[92:93], v[156:157], v[10:11] op_sel:[0,1,0] op_sel_hi:[1,1,1]
	v_pk_fma_f32 v[18:19], v[94:95], v[156:157], v[8:9] op_sel:[0,1,0] op_sel_hi:[1,1,1]
	v_add_f32_dpp v15, v24, v24 row_ror:8 row_mask:0xf bank_mask:0xf bound_ctrl:1
	ds_read_b128 v[76:79], v48 offset:4096
	s_nop 0
	v_add_f32_dpp v15, v15, v15 row_ror:4 row_mask:0xf bank_mask:0xf bound_ctrl:1
	ds_read_b128 v[128:131], v48 offset:3328
	ds_read_b128 v[132:135], v48 offset:3584
	v_add_f32_dpp v15, v15, v15 row_ror:2 row_mask:0xf bank_mask:0xf bound_ctrl:1
	ds_read_b128 v[136:139], v48 offset:3840
	ds_read_b128 v[160:163], v49 offset:16
	v_add_f32_dpp v30, v15, v15 row_ror:1 row_mask:0xf bank_mask:0xf bound_ctrl:1
	v_pk_fma_f32 v[10:11], v[96:97], v[30:31], v[16:17] op_sel_hi:[1,0,1] neg_lo:[0,1,0] neg_hi:[0,1,0]
	v_pk_fma_f32 v[8:9], v[98:99], v[30:31], v[18:19] op_sel_hi:[1,0,1] neg_lo:[0,1,0] neg_hi:[0,1,0]
	v_pk_mul_f32 v[26:27], v[10:11], v[100:101] op_sel:[0,0] op_sel_hi:[0,1]
	v_pk_fma_f32 v[26:27], v[10:11], v[102:103], v[26:27] op_sel:[1,0,0] op_sel_hi:[1,1,1]
	v_pk_fma_f32 v[26:27], v[8:9], v[104:105], v[26:27] op_sel:[0,0,0] op_sel_hi:[0,1,1]
	v_pk_fma_f32 v[26:27], v[8:9], v[106:107], v[26:27] op_sel:[1,0,0] op_sel_hi:[1,1,1]
	v_pk_fma_f32 v[16:17], v[108:109], v[158:159], v[10:11] op_sel_hi:[1,0,1]
	v_pk_fma_f32 v[18:19], v[110:111], v[158:159], v[8:9] op_sel_hi:[1,0,1]
	v_add_f32_dpp v15, v26, v26 row_ror:8 row_mask:0xf bank_mask:0xf bound_ctrl:1
	ds_read_b128 v[92:95], v48 offset:5120
	s_nop 0
	v_add_f32_dpp v15, v15, v15 row_ror:4 row_mask:0xf bank_mask:0xf bound_ctrl:1
	ds_read_b128 v[80:83], v48 offset:4352
	ds_read_b128 v[84:87], v48 offset:4608
	v_add_f32_dpp v15, v15, v15 row_ror:2 row_mask:0xf bank_mask:0xf bound_ctrl:1
	ds_read_b128 v[88:91], v48 offset:4864
	ds_write2st64_b32 v50, v25, v27 offset0:0 offset1:4
	v_add_f32_dpp v30, v15, v15 row_ror:1 row_mask:0xf bank_mask:0xf bound_ctrl:1
	s_waitcnt lgkmcnt(5)
	v_pk_fma_f32 v[10:11], v[112:113], v[30:31], v[16:17] op_sel_hi:[1,0,1] neg_lo:[0,1,0] neg_hi:[0,1,0]
	v_pk_fma_f32 v[8:9], v[114:115], v[30:31], v[18:19] op_sel_hi:[1,0,1] neg_lo:[0,1,0] neg_hi:[0,1,0]
	v_pk_mul_f32 v[24:25], v[10:11], v[116:117] op_sel:[0,0] op_sel_hi:[0,1]
	v_pk_fma_f32 v[24:25], v[10:11], v[118:119], v[24:25] op_sel:[1,0,0] op_sel_hi:[1,1,1]
	v_pk_fma_f32 v[24:25], v[8:9], v[120:121], v[24:25] op_sel:[0,0,0] op_sel_hi:[0,1,1]
	v_pk_fma_f32 v[24:25], v[8:9], v[122:123], v[24:25] op_sel:[1,0,0] op_sel_hi:[1,1,1]
	v_pk_fma_f32 v[16:17], v[124:125], v[158:159], v[10:11] op_sel:[0,1,0] op_sel_hi:[1,1,1]
	v_pk_fma_f32 v[18:19], v[126:127], v[158:159], v[8:9] op_sel:[0,1,0] op_sel_hi:[1,1,1]
	v_add_f32_dpp v15, v24, v24 row_ror:8 row_mask:0xf bank_mask:0xf bound_ctrl:1
	ds_read_b128 v[108:111], v48 offset:6144
	s_nop 0
	v_add_f32_dpp v15, v15, v15 row_ror:4 row_mask:0xf bank_mask:0xf bound_ctrl:1
	ds_read_b128 v[96:99], v48 offset:5376
	ds_read_b128 v[100:103], v48 offset:5632
	v_add_f32_dpp v15, v15, v15 row_ror:2 row_mask:0xf bank_mask:0xf bound_ctrl:1
	ds_read_b128 v[104:107], v48 offset:5888
	s_nop 0
	v_add_f32_dpp v30, v15, v15 row_ror:1 row_mask:0xf bank_mask:0xf bound_ctrl:1
	v_pk_fma_f32 v[10:11], v[128:129], v[30:31], v[16:17] op_sel_hi:[1,0,1] neg_lo:[0,1,0] neg_hi:[0,1,0]
	v_pk_fma_f32 v[8:9], v[130:131], v[30:31], v[18:19] op_sel_hi:[1,0,1] neg_lo:[0,1,0] neg_hi:[0,1,0]
	v_pk_mul_f32 v[26:27], v[10:11], v[132:133] op_sel:[0,0] op_sel_hi:[0,1]
	v_pk_fma_f32 v[26:27], v[10:11], v[134:135], v[26:27] op_sel:[1,0,0] op_sel_hi:[1,1,1]
	v_pk_fma_f32 v[26:27], v[8:9], v[136:137], v[26:27] op_sel:[0,0,0] op_sel_hi:[0,1,1]
	v_pk_fma_f32 v[26:27], v[8:9], v[138:139], v[26:27] op_sel:[1,0,0] op_sel_hi:[1,1,1]
	v_pk_fma_f32 v[16:17], v[76:77], v[160:161], v[10:11] op_sel_hi:[1,0,1]
	v_pk_fma_f32 v[18:19], v[78:79], v[160:161], v[8:9] op_sel_hi:[1,0,1]
	v_add_f32_dpp v15, v26, v26 row_ror:8 row_mask:0xf bank_mask:0xf bound_ctrl:1
	ds_read_b128 v[124:127], v48 offset:7168
	s_nop 0
	v_add_f32_dpp v15, v15, v15 row_ror:4 row_mask:0xf bank_mask:0xf bound_ctrl:1
	ds_read_b128 v[112:115], v48 offset:6400
	ds_read_b128 v[116:119], v48 offset:6656
	v_add_f32_dpp v15, v15, v15 row_ror:2 row_mask:0xf bank_mask:0xf bound_ctrl:1
	ds_read_b128 v[120:123], v48 offset:6912
	ds_write2st64_b32 v50, v25, v27 offset0:8 offset1:12
	v_add_f32_dpp v30, v15, v15 row_ror:1 row_mask:0xf bank_mask:0xf bound_ctrl:1
	s_waitcnt lgkmcnt(5)
	v_pk_fma_f32 v[10:11], v[80:81], v[30:31], v[16:17] op_sel_hi:[1,0,1] neg_lo:[0,1,0] neg_hi:[0,1,0]
	v_pk_fma_f32 v[8:9], v[82:83], v[30:31], v[18:19] op_sel_hi:[1,0,1] neg_lo:[0,1,0] neg_hi:[0,1,0]
	v_pk_mul_f32 v[24:25], v[10:11], v[84:85] op_sel:[0,0] op_sel_hi:[0,1]
	v_pk_fma_f32 v[24:25], v[10:11], v[86:87], v[24:25] op_sel:[1,0,0] op_sel_hi:[1,1,1]
	v_pk_fma_f32 v[24:25], v[8:9], v[88:89], v[24:25] op_sel:[0,0,0] op_sel_hi:[0,1,1]
	v_pk_fma_f32 v[24:25], v[8:9], v[90:91], v[24:25] op_sel:[1,0,0] op_sel_hi:[1,1,1]
	v_pk_fma_f32 v[16:17], v[92:93], v[160:161], v[10:11] op_sel:[0,1,0] op_sel_hi:[1,1,1]
	v_pk_fma_f32 v[18:19], v[94:95], v[160:161], v[8:9] op_sel:[0,1,0] op_sel_hi:[1,1,1]
	v_add_f32_dpp v15, v24, v24 row_ror:8 row_mask:0xf bank_mask:0xf bound_ctrl:1
	ds_read_b128 v[76:79], v48 offset:8192
	s_nop 0
	v_add_f32_dpp v15, v15, v15 row_ror:4 row_mask:0xf bank_mask:0xf bound_ctrl:1
	ds_read_b128 v[128:131], v48 offset:7424
	ds_read_b128 v[132:135], v48 offset:7680
	v_add_f32_dpp v15, v15, v15 row_ror:2 row_mask:0xf bank_mask:0xf bound_ctrl:1
	ds_read_b128 v[136:139], v48 offset:7936
	ds_read_b128 v[156:159], v49 offset:32
	v_add_f32_dpp v30, v15, v15 row_ror:1 row_mask:0xf bank_mask:0xf bound_ctrl:1
	v_pk_fma_f32 v[10:11], v[96:97], v[30:31], v[16:17] op_sel_hi:[1,0,1] neg_lo:[0,1,0] neg_hi:[0,1,0]
	v_pk_fma_f32 v[8:9], v[98:99], v[30:31], v[18:19] op_sel_hi:[1,0,1] neg_lo:[0,1,0] neg_hi:[0,1,0]
	v_pk_mul_f32 v[26:27], v[10:11], v[100:101] op_sel:[0,0] op_sel_hi:[0,1]
	v_pk_fma_f32 v[26:27], v[10:11], v[102:103], v[26:27] op_sel:[1,0,0] op_sel_hi:[1,1,1]
	v_pk_fma_f32 v[26:27], v[8:9], v[104:105], v[26:27] op_sel:[0,0,0] op_sel_hi:[0,1,1]
	v_pk_fma_f32 v[26:27], v[8:9], v[106:107], v[26:27] op_sel:[1,0,0] op_sel_hi:[1,1,1]
	v_pk_fma_f32 v[16:17], v[108:109], v[162:163], v[10:11] op_sel_hi:[1,0,1]
	v_pk_fma_f32 v[18:19], v[110:111], v[162:163], v[8:9] op_sel_hi:[1,0,1]
	v_add_f32_dpp v15, v26, v26 row_ror:8 row_mask:0xf bank_mask:0xf bound_ctrl:1
	ds_read_b128 v[92:95], v48 offset:9216
	s_nop 0
	v_add_f32_dpp v15, v15, v15 row_ror:4 row_mask:0xf bank_mask:0xf bound_ctrl:1
	ds_read_b128 v[80:83], v48 offset:8448
	ds_read_b128 v[84:87], v48 offset:8704
	v_add_f32_dpp v15, v15, v15 row_ror:2 row_mask:0xf bank_mask:0xf bound_ctrl:1
	ds_read_b128 v[88:91], v48 offset:8960
	ds_write2st64_b32 v50, v25, v27 offset0:16 offset1:20
	v_add_f32_dpp v30, v15, v15 row_ror:1 row_mask:0xf bank_mask:0xf bound_ctrl:1
	s_waitcnt lgkmcnt(5)
	v_pk_fma_f32 v[10:11], v[112:113], v[30:31], v[16:17] op_sel_hi:[1,0,1] neg_lo:[0,1,0] neg_hi:[0,1,0]
	v_pk_fma_f32 v[8:9], v[114:115], v[30:31], v[18:19] op_sel_hi:[1,0,1] neg_lo:[0,1,0] neg_hi:[0,1,0]
	v_pk_mul_f32 v[24:25], v[10:11], v[116:117] op_sel:[0,0] op_sel_hi:[0,1]
	v_pk_fma_f32 v[24:25], v[10:11], v[118:119], v[24:25] op_sel:[1,0,0] op_sel_hi:[1,1,1]
	v_pk_fma_f32 v[24:25], v[8:9], v[120:121], v[24:25] op_sel:[0,0,0] op_sel_hi:[0,1,1]
	v_pk_fma_f32 v[24:25], v[8:9], v[122:123], v[24:25] op_sel:[1,0,0] op_sel_hi:[1,1,1]
	v_pk_fma_f32 v[16:17], v[124:125], v[162:163], v[10:11] op_sel:[0,1,0] op_sel_hi:[1,1,1]
	v_pk_fma_f32 v[18:19], v[126:127], v[162:163], v[8:9] op_sel:[0,1,0] op_sel_hi:[1,1,1]
	v_add_f32_dpp v15, v24, v24 row_ror:8 row_mask:0xf bank_mask:0xf bound_ctrl:1
	ds_read_b128 v[108:111], v48 offset:10240
	s_nop 0
	v_add_f32_dpp v15, v15, v15 row_ror:4 row_mask:0xf bank_mask:0xf bound_ctrl:1
	ds_read_b128 v[96:99], v48 offset:9472
	ds_read_b128 v[100:103], v48 offset:9728
	v_add_f32_dpp v15, v15, v15 row_ror:2 row_mask:0xf bank_mask:0xf bound_ctrl:1
	ds_read_b128 v[104:107], v48 offset:9984
	s_nop 0
	v_add_f32_dpp v30, v15, v15 row_ror:1 row_mask:0xf bank_mask:0xf bound_ctrl:1
	v_pk_fma_f32 v[10:11], v[128:129], v[30:31], v[16:17] op_sel_hi:[1,0,1] neg_lo:[0,1,0] neg_hi:[0,1,0]
	v_pk_fma_f32 v[8:9], v[130:131], v[30:31], v[18:19] op_sel_hi:[1,0,1] neg_lo:[0,1,0] neg_hi:[0,1,0]
	v_pk_mul_f32 v[26:27], v[10:11], v[132:133] op_sel:[0,0] op_sel_hi:[0,1]
	v_pk_fma_f32 v[26:27], v[10:11], v[134:135], v[26:27] op_sel:[1,0,0] op_sel_hi:[1,1,1]
	v_pk_fma_f32 v[26:27], v[8:9], v[136:137], v[26:27] op_sel:[0,0,0] op_sel_hi:[0,1,1]
	v_pk_fma_f32 v[26:27], v[8:9], v[138:139], v[26:27] op_sel:[1,0,0] op_sel_hi:[1,1,1]
	v_pk_fma_f32 v[16:17], v[76:77], v[156:157], v[10:11] op_sel_hi:[1,0,1]
	v_pk_fma_f32 v[18:19], v[78:79], v[156:157], v[8:9] op_sel_hi:[1,0,1]
	v_add_f32_dpp v15, v26, v26 row_ror:8 row_mask:0xf bank_mask:0xf bound_ctrl:1
	ds_read_b128 v[124:127], v48 offset:11264
	s_nop 0
	v_add_f32_dpp v15, v15, v15 row_ror:4 row_mask:0xf bank_mask:0xf bound_ctrl:1
	ds_read_b128 v[112:115], v48 offset:10496
	ds_read_b128 v[116:119], v48 offset:10752
	v_add_f32_dpp v15, v15, v15 row_ror:2 row_mask:0xf bank_mask:0xf bound_ctrl:1
	ds_read_b128 v[120:123], v48 offset:11008
	ds_write2st64_b32 v50, v25, v27 offset0:24 offset1:28
	v_add_f32_dpp v30, v15, v15 row_ror:1 row_mask:0xf bank_mask:0xf bound_ctrl:1
	s_waitcnt lgkmcnt(5)
	v_pk_fma_f32 v[10:11], v[80:81], v[30:31], v[16:17] op_sel_hi:[1,0,1] neg_lo:[0,1,0] neg_hi:[0,1,0]
	v_pk_fma_f32 v[8:9], v[82:83], v[30:31], v[18:19] op_sel_hi:[1,0,1] neg_lo:[0,1,0] neg_hi:[0,1,0]
	v_pk_mul_f32 v[24:25], v[10:11], v[84:85] op_sel:[0,0] op_sel_hi:[0,1]
	v_pk_fma_f32 v[24:25], v[10:11], v[86:87], v[24:25] op_sel:[1,0,0] op_sel_hi:[1,1,1]
	v_pk_fma_f32 v[24:25], v[8:9], v[88:89], v[24:25] op_sel:[0,0,0] op_sel_hi:[0,1,1]
	v_pk_fma_f32 v[24:25], v[8:9], v[90:91], v[24:25] op_sel:[1,0,0] op_sel_hi:[1,1,1]
	v_pk_fma_f32 v[16:17], v[92:93], v[156:157], v[10:11] op_sel:[0,1,0] op_sel_hi:[1,1,1]
	v_pk_fma_f32 v[18:19], v[94:95], v[156:157], v[8:9] op_sel:[0,1,0] op_sel_hi:[1,1,1]
	v_add_f32_dpp v15, v24, v24 row_ror:8 row_mask:0xf bank_mask:0xf bound_ctrl:1
	ds_read_b128 v[76:79], v48 offset:12288
	s_nop 0
	v_add_f32_dpp v15, v15, v15 row_ror:4 row_mask:0xf bank_mask:0xf bound_ctrl:1
	ds_read_b128 v[128:131], v48 offset:11520
	ds_read_b128 v[132:135], v48 offset:11776
	v_add_f32_dpp v15, v15, v15 row_ror:2 row_mask:0xf bank_mask:0xf bound_ctrl:1
	ds_read_b128 v[136:139], v48 offset:12032
	ds_read_b128 v[160:163], v49 offset:48
	v_add_f32_dpp v30, v15, v15 row_ror:1 row_mask:0xf bank_mask:0xf bound_ctrl:1
	v_pk_fma_f32 v[10:11], v[96:97], v[30:31], v[16:17] op_sel_hi:[1,0,1] neg_lo:[0,1,0] neg_hi:[0,1,0]
	v_pk_fma_f32 v[8:9], v[98:99], v[30:31], v[18:19] op_sel_hi:[1,0,1] neg_lo:[0,1,0] neg_hi:[0,1,0]
	v_pk_mul_f32 v[26:27], v[10:11], v[100:101] op_sel:[0,0] op_sel_hi:[0,1]
	v_pk_fma_f32 v[26:27], v[10:11], v[102:103], v[26:27] op_sel:[1,0,0] op_sel_hi:[1,1,1]
	v_pk_fma_f32 v[26:27], v[8:9], v[104:105], v[26:27] op_sel:[0,0,0] op_sel_hi:[0,1,1]
	v_pk_fma_f32 v[26:27], v[8:9], v[106:107], v[26:27] op_sel:[1,0,0] op_sel_hi:[1,1,1]
	v_pk_fma_f32 v[16:17], v[108:109], v[158:159], v[10:11] op_sel_hi:[1,0,1]
	v_pk_fma_f32 v[18:19], v[110:111], v[158:159], v[8:9] op_sel_hi:[1,0,1]
	v_add_f32_dpp v15, v26, v26 row_ror:8 row_mask:0xf bank_mask:0xf bound_ctrl:1
	ds_read_b128 v[92:95], v48 offset:13312
	s_nop 0
	v_add_f32_dpp v15, v15, v15 row_ror:4 row_mask:0xf bank_mask:0xf bound_ctrl:1
	ds_read_b128 v[80:83], v48 offset:12544
	ds_read_b128 v[84:87], v48 offset:12800
	v_add_f32_dpp v15, v15, v15 row_ror:2 row_mask:0xf bank_mask:0xf bound_ctrl:1
	ds_read_b128 v[88:91], v48 offset:13056
	ds_write2st64_b32 v50, v25, v27 offset0:32 offset1:36
	v_add_f32_dpp v30, v15, v15 row_ror:1 row_mask:0xf bank_mask:0xf bound_ctrl:1
	s_waitcnt lgkmcnt(5)
	v_pk_fma_f32 v[10:11], v[112:113], v[30:31], v[16:17] op_sel_hi:[1,0,1] neg_lo:[0,1,0] neg_hi:[0,1,0]
	v_pk_fma_f32 v[8:9], v[114:115], v[30:31], v[18:19] op_sel_hi:[1,0,1] neg_lo:[0,1,0] neg_hi:[0,1,0]
	v_pk_mul_f32 v[24:25], v[10:11], v[116:117] op_sel:[0,0] op_sel_hi:[0,1]
	v_pk_fma_f32 v[24:25], v[10:11], v[118:119], v[24:25] op_sel:[1,0,0] op_sel_hi:[1,1,1]
	v_pk_fma_f32 v[24:25], v[8:9], v[120:121], v[24:25] op_sel:[0,0,0] op_sel_hi:[0,1,1]
	v_pk_fma_f32 v[24:25], v[8:9], v[122:123], v[24:25] op_sel:[1,0,0] op_sel_hi:[1,1,1]
	v_pk_fma_f32 v[16:17], v[124:125], v[158:159], v[10:11] op_sel:[0,1,0] op_sel_hi:[1,1,1]
	v_pk_fma_f32 v[18:19], v[126:127], v[158:159], v[8:9] op_sel:[0,1,0] op_sel_hi:[1,1,1]
	v_add_f32_dpp v15, v24, v24 row_ror:8 row_mask:0xf bank_mask:0xf bound_ctrl:1
	ds_read_b128 v[108:111], v48 offset:14336
	s_nop 0
	v_add_f32_dpp v15, v15, v15 row_ror:4 row_mask:0xf bank_mask:0xf bound_ctrl:1
	ds_read_b128 v[96:99], v48 offset:13568
	ds_read_b128 v[100:103], v48 offset:13824
	v_add_f32_dpp v15, v15, v15 row_ror:2 row_mask:0xf bank_mask:0xf bound_ctrl:1
	ds_read_b128 v[104:107], v48 offset:14080
	s_nop 0
	v_add_f32_dpp v30, v15, v15 row_ror:1 row_mask:0xf bank_mask:0xf bound_ctrl:1
	v_pk_fma_f32 v[10:11], v[128:129], v[30:31], v[16:17] op_sel_hi:[1,0,1] neg_lo:[0,1,0] neg_hi:[0,1,0]
	v_pk_fma_f32 v[8:9], v[130:131], v[30:31], v[18:19] op_sel_hi:[1,0,1] neg_lo:[0,1,0] neg_hi:[0,1,0]
	v_pk_mul_f32 v[26:27], v[10:11], v[132:133] op_sel:[0,0] op_sel_hi:[0,1]
	v_pk_fma_f32 v[26:27], v[10:11], v[134:135], v[26:27] op_sel:[1,0,0] op_sel_hi:[1,1,1]
	v_pk_fma_f32 v[26:27], v[8:9], v[136:137], v[26:27] op_sel:[0,0,0] op_sel_hi:[0,1,1]
	v_pk_fma_f32 v[26:27], v[8:9], v[138:139], v[26:27] op_sel:[1,0,0] op_sel_hi:[1,1,1]
	v_pk_fma_f32 v[16:17], v[76:77], v[160:161], v[10:11] op_sel_hi:[1,0,1]
	v_pk_fma_f32 v[18:19], v[78:79], v[160:161], v[8:9] op_sel_hi:[1,0,1]
	v_add_f32_dpp v15, v26, v26 row_ror:8 row_mask:0xf bank_mask:0xf bound_ctrl:1
	ds_read_b128 v[124:127], v48 offset:15360
	s_nop 0
	v_add_f32_dpp v15, v15, v15 row_ror:4 row_mask:0xf bank_mask:0xf bound_ctrl:1
	ds_read_b128 v[112:115], v48 offset:14592
	ds_read_b128 v[116:119], v48 offset:14848
	v_add_f32_dpp v15, v15, v15 row_ror:2 row_mask:0xf bank_mask:0xf bound_ctrl:1
	ds_read_b128 v[120:123], v48 offset:15104
	ds_write2st64_b32 v50, v25, v27 offset0:40 offset1:44
	v_add_f32_dpp v30, v15, v15 row_ror:1 row_mask:0xf bank_mask:0xf bound_ctrl:1
	s_waitcnt lgkmcnt(5)
	v_pk_fma_f32 v[10:11], v[80:81], v[30:31], v[16:17] op_sel_hi:[1,0,1] neg_lo:[0,1,0] neg_hi:[0,1,0]
	v_pk_fma_f32 v[8:9], v[82:83], v[30:31], v[18:19] op_sel_hi:[1,0,1] neg_lo:[0,1,0] neg_hi:[0,1,0]
	v_pk_mul_f32 v[24:25], v[10:11], v[84:85] op_sel:[0,0] op_sel_hi:[0,1]
	v_pk_fma_f32 v[24:25], v[10:11], v[86:87], v[24:25] op_sel:[1,0,0] op_sel_hi:[1,1,1]
	v_pk_fma_f32 v[24:25], v[8:9], v[88:89], v[24:25] op_sel:[0,0,0] op_sel_hi:[0,1,1]
	v_pk_fma_f32 v[24:25], v[8:9], v[90:91], v[24:25] op_sel:[1,0,0] op_sel_hi:[1,1,1]
	v_pk_fma_f32 v[16:17], v[92:93], v[160:161], v[10:11] op_sel:[0,1,0] op_sel_hi:[1,1,1]
	v_pk_fma_f32 v[18:19], v[94:95], v[160:161], v[8:9] op_sel:[0,1,0] op_sel_hi:[1,1,1]
	v_add_f32_dpp v15, v24, v24 row_ror:8 row_mask:0xf bank_mask:0xf bound_ctrl:1
	ds_read_b128 v[76:79], v48 offset:16384
	s_nop 0
	v_add_f32_dpp v15, v15, v15 row_ror:4 row_mask:0xf bank_mask:0xf bound_ctrl:1
	ds_read_b128 v[128:131], v48 offset:15616
	ds_read_b128 v[132:135], v48 offset:15872
	v_add_f32_dpp v15, v15, v15 row_ror:2 row_mask:0xf bank_mask:0xf bound_ctrl:1
	ds_read_b128 v[136:139], v48 offset:16128
	ds_read_b128 v[156:159], v49 offset:64
	v_add_f32_dpp v30, v15, v15 row_ror:1 row_mask:0xf bank_mask:0xf bound_ctrl:1
	v_pk_fma_f32 v[10:11], v[96:97], v[30:31], v[16:17] op_sel_hi:[1,0,1] neg_lo:[0,1,0] neg_hi:[0,1,0]
	v_pk_fma_f32 v[8:9], v[98:99], v[30:31], v[18:19] op_sel_hi:[1,0,1] neg_lo:[0,1,0] neg_hi:[0,1,0]
	v_pk_mul_f32 v[26:27], v[10:11], v[100:101] op_sel:[0,0] op_sel_hi:[0,1]
	v_pk_fma_f32 v[26:27], v[10:11], v[102:103], v[26:27] op_sel:[1,0,0] op_sel_hi:[1,1,1]
	v_pk_fma_f32 v[26:27], v[8:9], v[104:105], v[26:27] op_sel:[0,0,0] op_sel_hi:[0,1,1]
	v_pk_fma_f32 v[26:27], v[8:9], v[106:107], v[26:27] op_sel:[1,0,0] op_sel_hi:[1,1,1]
	v_pk_fma_f32 v[16:17], v[108:109], v[162:163], v[10:11] op_sel_hi:[1,0,1]
	v_pk_fma_f32 v[18:19], v[110:111], v[162:163], v[8:9] op_sel_hi:[1,0,1]
	v_add_f32_dpp v15, v26, v26 row_ror:8 row_mask:0xf bank_mask:0xf bound_ctrl:1
	ds_read_b128 v[92:95], v48 offset:17408
	s_nop 0
	v_add_f32_dpp v15, v15, v15 row_ror:4 row_mask:0xf bank_mask:0xf bound_ctrl:1
	ds_read_b128 v[80:83], v48 offset:16640
	ds_read_b128 v[84:87], v48 offset:16896
	v_add_f32_dpp v15, v15, v15 row_ror:2 row_mask:0xf bank_mask:0xf bound_ctrl:1
	ds_read_b128 v[88:91], v48 offset:17152
	ds_write2st64_b32 v50, v25, v27 offset0:48 offset1:52
	v_add_f32_dpp v30, v15, v15 row_ror:1 row_mask:0xf bank_mask:0xf bound_ctrl:1
	s_waitcnt lgkmcnt(5)
	v_pk_fma_f32 v[10:11], v[112:113], v[30:31], v[16:17] op_sel_hi:[1,0,1] neg_lo:[0,1,0] neg_hi:[0,1,0]
	v_pk_fma_f32 v[8:9], v[114:115], v[30:31], v[18:19] op_sel_hi:[1,0,1] neg_lo:[0,1,0] neg_hi:[0,1,0]
	v_pk_mul_f32 v[24:25], v[10:11], v[116:117] op_sel:[0,0] op_sel_hi:[0,1]
	v_pk_fma_f32 v[24:25], v[10:11], v[118:119], v[24:25] op_sel:[1,0,0] op_sel_hi:[1,1,1]
	v_pk_fma_f32 v[24:25], v[8:9], v[120:121], v[24:25] op_sel:[0,0,0] op_sel_hi:[0,1,1]
	v_pk_fma_f32 v[24:25], v[8:9], v[122:123], v[24:25] op_sel:[1,0,0] op_sel_hi:[1,1,1]
	v_pk_fma_f32 v[16:17], v[124:125], v[162:163], v[10:11] op_sel:[0,1,0] op_sel_hi:[1,1,1]
	v_pk_fma_f32 v[18:19], v[126:127], v[162:163], v[8:9] op_sel:[0,1,0] op_sel_hi:[1,1,1]
	v_add_f32_dpp v15, v24, v24 row_ror:8 row_mask:0xf bank_mask:0xf bound_ctrl:1
	ds_read_b128 v[108:111], v48 offset:18432
	s_nop 0
	v_add_f32_dpp v15, v15, v15 row_ror:4 row_mask:0xf bank_mask:0xf bound_ctrl:1
	ds_read_b128 v[96:99], v48 offset:17664
	ds_read_b128 v[100:103], v48 offset:17920
	v_add_f32_dpp v15, v15, v15 row_ror:2 row_mask:0xf bank_mask:0xf bound_ctrl:1
	ds_read_b128 v[104:107], v48 offset:18176
	s_nop 0
	v_add_f32_dpp v30, v15, v15 row_ror:1 row_mask:0xf bank_mask:0xf bound_ctrl:1
	v_pk_fma_f32 v[10:11], v[128:129], v[30:31], v[16:17] op_sel_hi:[1,0,1] neg_lo:[0,1,0] neg_hi:[0,1,0]
	v_pk_fma_f32 v[8:9], v[130:131], v[30:31], v[18:19] op_sel_hi:[1,0,1] neg_lo:[0,1,0] neg_hi:[0,1,0]
	v_pk_mul_f32 v[26:27], v[10:11], v[132:133] op_sel:[0,0] op_sel_hi:[0,1]
	v_pk_fma_f32 v[26:27], v[10:11], v[134:135], v[26:27] op_sel:[1,0,0] op_sel_hi:[1,1,1]
	v_pk_fma_f32 v[26:27], v[8:9], v[136:137], v[26:27] op_sel:[0,0,0] op_sel_hi:[0,1,1]
	v_pk_fma_f32 v[26:27], v[8:9], v[138:139], v[26:27] op_sel:[1,0,0] op_sel_hi:[1,1,1]
	v_pk_fma_f32 v[16:17], v[76:77], v[156:157], v[10:11] op_sel_hi:[1,0,1]
	v_pk_fma_f32 v[18:19], v[78:79], v[156:157], v[8:9] op_sel_hi:[1,0,1]
	v_add_f32_dpp v15, v26, v26 row_ror:8 row_mask:0xf bank_mask:0xf bound_ctrl:1
	ds_read_b128 v[124:127], v48 offset:19456
	s_nop 0
	v_add_f32_dpp v15, v15, v15 row_ror:4 row_mask:0xf bank_mask:0xf bound_ctrl:1
	ds_read_b128 v[112:115], v48 offset:18688
	ds_read_b128 v[116:119], v48 offset:18944
	v_add_f32_dpp v15, v15, v15 row_ror:2 row_mask:0xf bank_mask:0xf bound_ctrl:1
	ds_read_b128 v[120:123], v48 offset:19200
	ds_write2st64_b32 v50, v25, v27 offset0:56 offset1:60
	v_add_f32_dpp v30, v15, v15 row_ror:1 row_mask:0xf bank_mask:0xf bound_ctrl:1
	s_waitcnt lgkmcnt(5)
	v_pk_fma_f32 v[10:11], v[80:81], v[30:31], v[16:17] op_sel_hi:[1,0,1] neg_lo:[0,1,0] neg_hi:[0,1,0]
	v_pk_fma_f32 v[8:9], v[82:83], v[30:31], v[18:19] op_sel_hi:[1,0,1] neg_lo:[0,1,0] neg_hi:[0,1,0]
	v_pk_mul_f32 v[24:25], v[10:11], v[84:85] op_sel:[0,0] op_sel_hi:[0,1]
	v_pk_fma_f32 v[24:25], v[10:11], v[86:87], v[24:25] op_sel:[1,0,0] op_sel_hi:[1,1,1]
	v_pk_fma_f32 v[24:25], v[8:9], v[88:89], v[24:25] op_sel:[0,0,0] op_sel_hi:[0,1,1]
	v_pk_fma_f32 v[24:25], v[8:9], v[90:91], v[24:25] op_sel:[1,0,0] op_sel_hi:[1,1,1]
	v_pk_fma_f32 v[16:17], v[92:93], v[156:157], v[10:11] op_sel:[0,1,0] op_sel_hi:[1,1,1]
	v_pk_fma_f32 v[18:19], v[94:95], v[156:157], v[8:9] op_sel:[0,1,0] op_sel_hi:[1,1,1]
	v_add_f32_dpp v15, v24, v24 row_ror:8 row_mask:0xf bank_mask:0xf bound_ctrl:1
	ds_read_b128 v[76:79], v48 offset:20480
	s_nop 0
	v_add_f32_dpp v15, v15, v15 row_ror:4 row_mask:0xf bank_mask:0xf bound_ctrl:1
	ds_read_b128 v[128:131], v48 offset:19712
	ds_read_b128 v[132:135], v48 offset:19968
	v_add_f32_dpp v15, v15, v15 row_ror:2 row_mask:0xf bank_mask:0xf bound_ctrl:1
	ds_read_b128 v[136:139], v48 offset:20224
	ds_read_b128 v[160:163], v49 offset:80
	v_add_f32_dpp v30, v15, v15 row_ror:1 row_mask:0xf bank_mask:0xf bound_ctrl:1
	v_pk_fma_f32 v[10:11], v[96:97], v[30:31], v[16:17] op_sel_hi:[1,0,1] neg_lo:[0,1,0] neg_hi:[0,1,0]
	v_pk_fma_f32 v[8:9], v[98:99], v[30:31], v[18:19] op_sel_hi:[1,0,1] neg_lo:[0,1,0] neg_hi:[0,1,0]
	v_pk_mul_f32 v[26:27], v[10:11], v[100:101] op_sel:[0,0] op_sel_hi:[0,1]
	v_pk_fma_f32 v[26:27], v[10:11], v[102:103], v[26:27] op_sel:[1,0,0] op_sel_hi:[1,1,1]
	v_pk_fma_f32 v[26:27], v[8:9], v[104:105], v[26:27] op_sel:[0,0,0] op_sel_hi:[0,1,1]
	v_pk_fma_f32 v[26:27], v[8:9], v[106:107], v[26:27] op_sel:[1,0,0] op_sel_hi:[1,1,1]
	v_pk_fma_f32 v[16:17], v[108:109], v[158:159], v[10:11] op_sel_hi:[1,0,1]
	v_pk_fma_f32 v[18:19], v[110:111], v[158:159], v[8:9] op_sel_hi:[1,0,1]
	v_add_f32_dpp v15, v26, v26 row_ror:8 row_mask:0xf bank_mask:0xf bound_ctrl:1
	ds_read_b128 v[92:95], v48 offset:21504
	s_nop 0
	v_add_f32_dpp v15, v15, v15 row_ror:4 row_mask:0xf bank_mask:0xf bound_ctrl:1
	ds_read_b128 v[80:83], v48 offset:20736
	ds_read_b128 v[84:87], v48 offset:20992
	v_add_f32_dpp v15, v15, v15 row_ror:2 row_mask:0xf bank_mask:0xf bound_ctrl:1
	ds_read_b128 v[88:91], v48 offset:21248
	ds_write2st64_b32 v50, v25, v27 offset0:64 offset1:68
	v_add_f32_dpp v30, v15, v15 row_ror:1 row_mask:0xf bank_mask:0xf bound_ctrl:1
	s_waitcnt lgkmcnt(5)
	v_pk_fma_f32 v[10:11], v[112:113], v[30:31], v[16:17] op_sel_hi:[1,0,1] neg_lo:[0,1,0] neg_hi:[0,1,0]
	v_pk_fma_f32 v[8:9], v[114:115], v[30:31], v[18:19] op_sel_hi:[1,0,1] neg_lo:[0,1,0] neg_hi:[0,1,0]
	v_pk_mul_f32 v[24:25], v[10:11], v[116:117] op_sel:[0,0] op_sel_hi:[0,1]
	v_pk_fma_f32 v[24:25], v[10:11], v[118:119], v[24:25] op_sel:[1,0,0] op_sel_hi:[1,1,1]
	v_pk_fma_f32 v[24:25], v[8:9], v[120:121], v[24:25] op_sel:[0,0,0] op_sel_hi:[0,1,1]
	v_pk_fma_f32 v[24:25], v[8:9], v[122:123], v[24:25] op_sel:[1,0,0] op_sel_hi:[1,1,1]
	v_pk_fma_f32 v[16:17], v[124:125], v[158:159], v[10:11] op_sel:[0,1,0] op_sel_hi:[1,1,1]
	v_pk_fma_f32 v[18:19], v[126:127], v[158:159], v[8:9] op_sel:[0,1,0] op_sel_hi:[1,1,1]
	v_add_f32_dpp v15, v24, v24 row_ror:8 row_mask:0xf bank_mask:0xf bound_ctrl:1
	ds_read_b128 v[108:111], v48 offset:22528
	s_nop 0
	v_add_f32_dpp v15, v15, v15 row_ror:4 row_mask:0xf bank_mask:0xf bound_ctrl:1
	ds_read_b128 v[96:99], v48 offset:21760
	ds_read_b128 v[100:103], v48 offset:22016
	v_add_f32_dpp v15, v15, v15 row_ror:2 row_mask:0xf bank_mask:0xf bound_ctrl:1
	ds_read_b128 v[104:107], v48 offset:22272
	s_nop 0
	v_add_f32_dpp v30, v15, v15 row_ror:1 row_mask:0xf bank_mask:0xf bound_ctrl:1
	v_pk_fma_f32 v[10:11], v[128:129], v[30:31], v[16:17] op_sel_hi:[1,0,1] neg_lo:[0,1,0] neg_hi:[0,1,0]
	v_pk_fma_f32 v[8:9], v[130:131], v[30:31], v[18:19] op_sel_hi:[1,0,1] neg_lo:[0,1,0] neg_hi:[0,1,0]
	v_pk_mul_f32 v[26:27], v[10:11], v[132:133] op_sel:[0,0] op_sel_hi:[0,1]
	v_pk_fma_f32 v[26:27], v[10:11], v[134:135], v[26:27] op_sel:[1,0,0] op_sel_hi:[1,1,1]
	v_pk_fma_f32 v[26:27], v[8:9], v[136:137], v[26:27] op_sel:[0,0,0] op_sel_hi:[0,1,1]
	v_pk_fma_f32 v[26:27], v[8:9], v[138:139], v[26:27] op_sel:[1,0,0] op_sel_hi:[1,1,1]
	v_pk_fma_f32 v[16:17], v[76:77], v[160:161], v[10:11] op_sel_hi:[1,0,1]
	v_pk_fma_f32 v[18:19], v[78:79], v[160:161], v[8:9] op_sel_hi:[1,0,1]
	v_add_f32_dpp v15, v26, v26 row_ror:8 row_mask:0xf bank_mask:0xf bound_ctrl:1
	ds_read_b128 v[124:127], v48 offset:23552
	s_nop 0
	v_add_f32_dpp v15, v15, v15 row_ror:4 row_mask:0xf bank_mask:0xf bound_ctrl:1
	ds_read_b128 v[112:115], v48 offset:22784
	ds_read_b128 v[116:119], v48 offset:23040
	v_add_f32_dpp v15, v15, v15 row_ror:2 row_mask:0xf bank_mask:0xf bound_ctrl:1
	ds_read_b128 v[120:123], v48 offset:23296
	ds_write2st64_b32 v50, v25, v27 offset0:72 offset1:76
	v_add_f32_dpp v30, v15, v15 row_ror:1 row_mask:0xf bank_mask:0xf bound_ctrl:1
	s_waitcnt lgkmcnt(5)
	v_pk_fma_f32 v[10:11], v[80:81], v[30:31], v[16:17] op_sel_hi:[1,0,1] neg_lo:[0,1,0] neg_hi:[0,1,0]
	v_pk_fma_f32 v[8:9], v[82:83], v[30:31], v[18:19] op_sel_hi:[1,0,1] neg_lo:[0,1,0] neg_hi:[0,1,0]
	v_pk_mul_f32 v[24:25], v[10:11], v[84:85] op_sel:[0,0] op_sel_hi:[0,1]
	v_pk_fma_f32 v[24:25], v[10:11], v[86:87], v[24:25] op_sel:[1,0,0] op_sel_hi:[1,1,1]
	v_pk_fma_f32 v[24:25], v[8:9], v[88:89], v[24:25] op_sel:[0,0,0] op_sel_hi:[0,1,1]
	v_pk_fma_f32 v[24:25], v[8:9], v[90:91], v[24:25] op_sel:[1,0,0] op_sel_hi:[1,1,1]
	v_pk_fma_f32 v[16:17], v[92:93], v[160:161], v[10:11] op_sel:[0,1,0] op_sel_hi:[1,1,1]
	v_pk_fma_f32 v[18:19], v[94:95], v[160:161], v[8:9] op_sel:[0,1,0] op_sel_hi:[1,1,1]
	v_add_f32_dpp v15, v24, v24 row_ror:8 row_mask:0xf bank_mask:0xf bound_ctrl:1
	ds_read_b128 v[76:79], v48 offset:24576
	s_nop 0
	v_add_f32_dpp v15, v15, v15 row_ror:4 row_mask:0xf bank_mask:0xf bound_ctrl:1
	ds_read_b128 v[128:131], v48 offset:23808
	ds_read_b128 v[132:135], v48 offset:24064
	v_add_f32_dpp v15, v15, v15 row_ror:2 row_mask:0xf bank_mask:0xf bound_ctrl:1
	ds_read_b128 v[136:139], v48 offset:24320
	ds_read_b128 v[156:159], v49 offset:96
	v_add_f32_dpp v30, v15, v15 row_ror:1 row_mask:0xf bank_mask:0xf bound_ctrl:1
	v_pk_fma_f32 v[10:11], v[96:97], v[30:31], v[16:17] op_sel_hi:[1,0,1] neg_lo:[0,1,0] neg_hi:[0,1,0]
	v_pk_fma_f32 v[8:9], v[98:99], v[30:31], v[18:19] op_sel_hi:[1,0,1] neg_lo:[0,1,0] neg_hi:[0,1,0]
	v_pk_mul_f32 v[26:27], v[10:11], v[100:101] op_sel:[0,0] op_sel_hi:[0,1]
	v_pk_fma_f32 v[26:27], v[10:11], v[102:103], v[26:27] op_sel:[1,0,0] op_sel_hi:[1,1,1]
	v_pk_fma_f32 v[26:27], v[8:9], v[104:105], v[26:27] op_sel:[0,0,0] op_sel_hi:[0,1,1]
	v_pk_fma_f32 v[26:27], v[8:9], v[106:107], v[26:27] op_sel:[1,0,0] op_sel_hi:[1,1,1]
	v_pk_fma_f32 v[16:17], v[108:109], v[162:163], v[10:11] op_sel_hi:[1,0,1]
	v_pk_fma_f32 v[18:19], v[110:111], v[162:163], v[8:9] op_sel_hi:[1,0,1]
	v_add_f32_dpp v15, v26, v26 row_ror:8 row_mask:0xf bank_mask:0xf bound_ctrl:1
	ds_read_b128 v[92:95], v48 offset:25600
	s_nop 0
	v_add_f32_dpp v15, v15, v15 row_ror:4 row_mask:0xf bank_mask:0xf bound_ctrl:1
	ds_read_b128 v[80:83], v48 offset:24832
	ds_read_b128 v[84:87], v48 offset:25088
	v_add_f32_dpp v15, v15, v15 row_ror:2 row_mask:0xf bank_mask:0xf bound_ctrl:1
	ds_read_b128 v[88:91], v48 offset:25344
	ds_write2st64_b32 v50, v25, v27 offset0:80 offset1:84
	v_add_f32_dpp v30, v15, v15 row_ror:1 row_mask:0xf bank_mask:0xf bound_ctrl:1
	s_waitcnt lgkmcnt(5)
	v_pk_fma_f32 v[10:11], v[112:113], v[30:31], v[16:17] op_sel_hi:[1,0,1] neg_lo:[0,1,0] neg_hi:[0,1,0]
	v_pk_fma_f32 v[8:9], v[114:115], v[30:31], v[18:19] op_sel_hi:[1,0,1] neg_lo:[0,1,0] neg_hi:[0,1,0]
	v_pk_mul_f32 v[24:25], v[10:11], v[116:117] op_sel:[0,0] op_sel_hi:[0,1]
	v_pk_fma_f32 v[24:25], v[10:11], v[118:119], v[24:25] op_sel:[1,0,0] op_sel_hi:[1,1,1]
	v_pk_fma_f32 v[24:25], v[8:9], v[120:121], v[24:25] op_sel:[0,0,0] op_sel_hi:[0,1,1]
	v_pk_fma_f32 v[24:25], v[8:9], v[122:123], v[24:25] op_sel:[1,0,0] op_sel_hi:[1,1,1]
	v_pk_fma_f32 v[16:17], v[124:125], v[162:163], v[10:11] op_sel:[0,1,0] op_sel_hi:[1,1,1]
	v_pk_fma_f32 v[18:19], v[126:127], v[162:163], v[8:9] op_sel:[0,1,0] op_sel_hi:[1,1,1]
	v_add_f32_dpp v15, v24, v24 row_ror:8 row_mask:0xf bank_mask:0xf bound_ctrl:1
	ds_read_b128 v[108:111], v48 offset:26624
	s_nop 0
	v_add_f32_dpp v15, v15, v15 row_ror:4 row_mask:0xf bank_mask:0xf bound_ctrl:1
	ds_read_b128 v[96:99], v48 offset:25856
	ds_read_b128 v[100:103], v48 offset:26112
	v_add_f32_dpp v15, v15, v15 row_ror:2 row_mask:0xf bank_mask:0xf bound_ctrl:1
	ds_read_b128 v[104:107], v48 offset:26368
	s_nop 0
	v_add_f32_dpp v30, v15, v15 row_ror:1 row_mask:0xf bank_mask:0xf bound_ctrl:1
	v_pk_fma_f32 v[10:11], v[128:129], v[30:31], v[16:17] op_sel_hi:[1,0,1] neg_lo:[0,1,0] neg_hi:[0,1,0]
	v_pk_fma_f32 v[8:9], v[130:131], v[30:31], v[18:19] op_sel_hi:[1,0,1] neg_lo:[0,1,0] neg_hi:[0,1,0]
	v_pk_mul_f32 v[26:27], v[10:11], v[132:133] op_sel:[0,0] op_sel_hi:[0,1]
	v_pk_fma_f32 v[26:27], v[10:11], v[134:135], v[26:27] op_sel:[1,0,0] op_sel_hi:[1,1,1]
	v_pk_fma_f32 v[26:27], v[8:9], v[136:137], v[26:27] op_sel:[0,0,0] op_sel_hi:[0,1,1]
	v_pk_fma_f32 v[26:27], v[8:9], v[138:139], v[26:27] op_sel:[1,0,0] op_sel_hi:[1,1,1]
	v_pk_fma_f32 v[16:17], v[76:77], v[156:157], v[10:11] op_sel_hi:[1,0,1]
	v_pk_fma_f32 v[18:19], v[78:79], v[156:157], v[8:9] op_sel_hi:[1,0,1]
	v_add_f32_dpp v15, v26, v26 row_ror:8 row_mask:0xf bank_mask:0xf bound_ctrl:1
	ds_read_b128 v[124:127], v48 offset:27648
	s_nop 0
	v_add_f32_dpp v15, v15, v15 row_ror:4 row_mask:0xf bank_mask:0xf bound_ctrl:1
	ds_read_b128 v[112:115], v48 offset:26880
	ds_read_b128 v[116:119], v48 offset:27136
	v_add_f32_dpp v15, v15, v15 row_ror:2 row_mask:0xf bank_mask:0xf bound_ctrl:1
	ds_read_b128 v[120:123], v48 offset:27392
	ds_write2st64_b32 v50, v25, v27 offset0:88 offset1:92
	v_add_f32_dpp v30, v15, v15 row_ror:1 row_mask:0xf bank_mask:0xf bound_ctrl:1
	s_waitcnt lgkmcnt(5)
	v_pk_fma_f32 v[10:11], v[80:81], v[30:31], v[16:17] op_sel_hi:[1,0,1] neg_lo:[0,1,0] neg_hi:[0,1,0]
	v_pk_fma_f32 v[8:9], v[82:83], v[30:31], v[18:19] op_sel_hi:[1,0,1] neg_lo:[0,1,0] neg_hi:[0,1,0]
	v_pk_mul_f32 v[24:25], v[10:11], v[84:85] op_sel:[0,0] op_sel_hi:[0,1]
	v_pk_fma_f32 v[24:25], v[10:11], v[86:87], v[24:25] op_sel:[1,0,0] op_sel_hi:[1,1,1]
	v_pk_fma_f32 v[24:25], v[8:9], v[88:89], v[24:25] op_sel:[0,0,0] op_sel_hi:[0,1,1]
	v_pk_fma_f32 v[24:25], v[8:9], v[90:91], v[24:25] op_sel:[1,0,0] op_sel_hi:[1,1,1]
	v_pk_fma_f32 v[16:17], v[92:93], v[156:157], v[10:11] op_sel:[0,1,0] op_sel_hi:[1,1,1]
	v_pk_fma_f32 v[18:19], v[94:95], v[156:157], v[8:9] op_sel:[0,1,0] op_sel_hi:[1,1,1]
	v_add_f32_dpp v15, v24, v24 row_ror:8 row_mask:0xf bank_mask:0xf bound_ctrl:1
	ds_read_b128 v[76:79], v48 offset:28672
	s_nop 0
	v_add_f32_dpp v15, v15, v15 row_ror:4 row_mask:0xf bank_mask:0xf bound_ctrl:1
	ds_read_b128 v[128:131], v48 offset:27904
	ds_read_b128 v[132:135], v48 offset:28160
	v_add_f32_dpp v15, v15, v15 row_ror:2 row_mask:0xf bank_mask:0xf bound_ctrl:1
	ds_read_b128 v[136:139], v48 offset:28416
	ds_read_b128 v[160:163], v49 offset:112
	v_add_f32_dpp v30, v15, v15 row_ror:1 row_mask:0xf bank_mask:0xf bound_ctrl:1
	ds_read_b128 v[56:59], v52
	v_pk_fma_f32 v[10:11], v[96:97], v[30:31], v[16:17] op_sel_hi:[1,0,1] neg_lo:[0,1,0] neg_hi:[0,1,0]
	v_pk_fma_f32 v[8:9], v[98:99], v[30:31], v[18:19] op_sel_hi:[1,0,1] neg_lo:[0,1,0] neg_hi:[0,1,0]
	v_pk_mul_f32 v[26:27], v[10:11], v[100:101] op_sel:[0,0] op_sel_hi:[0,1]
	v_pk_fma_f32 v[26:27], v[10:11], v[102:103], v[26:27] op_sel:[1,0,0] op_sel_hi:[1,1,1]
	v_pk_fma_f32 v[26:27], v[8:9], v[104:105], v[26:27] op_sel:[0,0,0] op_sel_hi:[0,1,1]
	v_pk_fma_f32 v[26:27], v[8:9], v[106:107], v[26:27] op_sel:[1,0,0] op_sel_hi:[1,1,1]
	v_pk_fma_f32 v[16:17], v[108:109], v[158:159], v[10:11] op_sel_hi:[1,0,1]
	v_pk_fma_f32 v[18:19], v[110:111], v[158:159], v[8:9] op_sel_hi:[1,0,1]
	v_add_f32_dpp v15, v26, v26 row_ror:8 row_mask:0xf bank_mask:0xf bound_ctrl:1
	ds_read_b128 v[92:95], v48 offset:29696
	s_nop 0
	v_add_f32_dpp v15, v15, v15 row_ror:4 row_mask:0xf bank_mask:0xf bound_ctrl:1
	ds_read_b128 v[80:83], v48 offset:28928
	ds_read_b128 v[84:87], v48 offset:29184
	v_add_f32_dpp v15, v15, v15 row_ror:2 row_mask:0xf bank_mask:0xf bound_ctrl:1
	ds_read_b128 v[88:91], v48 offset:29440
	ds_write2st64_b32 v50, v25, v27 offset0:96 offset1:100
	v_add_f32_dpp v30, v15, v15 row_ror:1 row_mask:0xf bank_mask:0xf bound_ctrl:1
	s_waitcnt lgkmcnt(5)
	v_min_u32_e32 v56, v56, v57
	v_min3_u32 v56, v56, v58, v59
	v_pk_fma_f32 v[10:11], v[112:113], v[30:31], v[16:17] op_sel_hi:[1,0,1] neg_lo:[0,1,0] neg_hi:[0,1,0]
	v_pk_fma_f32 v[8:9], v[114:115], v[30:31], v[18:19] op_sel_hi:[1,0,1] neg_lo:[0,1,0] neg_hi:[0,1,0]
	v_pk_mul_f32 v[24:25], v[10:11], v[116:117] op_sel:[0,0] op_sel_hi:[0,1]
	v_pk_fma_f32 v[24:25], v[10:11], v[118:119], v[24:25] op_sel:[1,0,0] op_sel_hi:[1,1,1]
	v_pk_fma_f32 v[24:25], v[8:9], v[120:121], v[24:25] op_sel:[0,0,0] op_sel_hi:[0,1,1]
	v_pk_fma_f32 v[24:25], v[8:9], v[122:123], v[24:25] op_sel:[1,0,0] op_sel_hi:[1,1,1]
	v_pk_fma_f32 v[16:17], v[124:125], v[158:159], v[10:11] op_sel:[0,1,0] op_sel_hi:[1,1,1]
	v_pk_fma_f32 v[18:19], v[126:127], v[158:159], v[8:9] op_sel:[0,1,0] op_sel_hi:[1,1,1]
	v_add_f32_dpp v15, v24, v24 row_ror:8 row_mask:0xf bank_mask:0xf bound_ctrl:1
	ds_read_b128 v[108:111], v48 offset:30720
	s_nop 0
	v_add_f32_dpp v15, v15, v15 row_ror:4 row_mask:0xf bank_mask:0xf bound_ctrl:1
	ds_read_b128 v[96:99], v48 offset:29952
	ds_read_b128 v[100:103], v48 offset:30208
	v_add_f32_dpp v15, v15, v15 row_ror:2 row_mask:0xf bank_mask:0xf bound_ctrl:1
	ds_read_b128 v[104:107], v48 offset:30464
	s_nop 0
	v_add_f32_dpp v30, v15, v15 row_ror:1 row_mask:0xf bank_mask:0xf bound_ctrl:1
	v_pk_fma_f32 v[10:11], v[128:129], v[30:31], v[16:17] op_sel_hi:[1,0,1] neg_lo:[0,1,0] neg_hi:[0,1,0]
	v_pk_fma_f32 v[8:9], v[130:131], v[30:31], v[18:19] op_sel_hi:[1,0,1] neg_lo:[0,1,0] neg_hi:[0,1,0]
	v_pk_mul_f32 v[26:27], v[10:11], v[132:133] op_sel:[0,0] op_sel_hi:[0,1]
	v_pk_fma_f32 v[26:27], v[10:11], v[134:135], v[26:27] op_sel:[1,0,0] op_sel_hi:[1,1,1]
	v_pk_fma_f32 v[26:27], v[8:9], v[136:137], v[26:27] op_sel:[0,0,0] op_sel_hi:[0,1,1]
	v_pk_fma_f32 v[26:27], v[8:9], v[138:139], v[26:27] op_sel:[1,0,0] op_sel_hi:[1,1,1]
	v_pk_fma_f32 v[16:17], v[76:77], v[160:161], v[10:11] op_sel_hi:[1,0,1]
	v_pk_fma_f32 v[18:19], v[78:79], v[160:161], v[8:9] op_sel_hi:[1,0,1]
	v_add_f32_dpp v15, v26, v26 row_ror:8 row_mask:0xf bank_mask:0xf bound_ctrl:1
	ds_read_b128 v[124:127], v48 offset:31744
	s_nop 0
	v_add_f32_dpp v15, v15, v15 row_ror:4 row_mask:0xf bank_mask:0xf bound_ctrl:1
	ds_read_b128 v[112:115], v48 offset:30976
	ds_read_b128 v[116:119], v48 offset:31232
	v_add_f32_dpp v15, v15, v15 row_ror:2 row_mask:0xf bank_mask:0xf bound_ctrl:1
	ds_read_b128 v[120:123], v48 offset:31488
	ds_read_b128 v[140:143], v48 offset:34560
	ds_write2st64_b32 v50, v25, v27 offset0:104 offset1:108
	v_add_f32_dpp v30, v15, v15 row_ror:1 row_mask:0xf bank_mask:0xf bound_ctrl:1
	v_readfirstlane_b32 s54, v56
	s_add_u32 s64, s6, 2
	s_cmp_lt_u32 s54, s64
	s_cbranch_scc1 .Lss_spin_1
.Lss_ok_1:
	s_waitcnt lgkmcnt(6)
	v_pk_fma_f32 v[10:11], v[80:81], v[30:31], v[16:17] op_sel_hi:[1,0,1] neg_lo:[0,1,0] neg_hi:[0,1,0]
	v_pk_fma_f32 v[8:9], v[82:83], v[30:31], v[18:19] op_sel_hi:[1,0,1] neg_lo:[0,1,0] neg_hi:[0,1,0]
	v_pk_mul_f32 v[24:25], v[10:11], v[84:85] op_sel:[0,0] op_sel_hi:[0,1]
	v_pk_fma_f32 v[24:25], v[10:11], v[86:87], v[24:25] op_sel:[1,0,0] op_sel_hi:[1,1,1]
	v_pk_fma_f32 v[24:25], v[8:9], v[88:89], v[24:25] op_sel:[0,0,0] op_sel_hi:[0,1,1]
	v_pk_fma_f32 v[24:25], v[8:9], v[90:91], v[24:25] op_sel:[1,0,0] op_sel_hi:[1,1,1]
	v_pk_fma_f32 v[16:17], v[92:93], v[160:161], v[10:11] op_sel:[0,1,0] op_sel_hi:[1,1,1]
	v_pk_fma_f32 v[18:19], v[94:95], v[160:161], v[8:9] op_sel:[0,1,0] op_sel_hi:[1,1,1]
	v_add_f32_dpp v15, v24, v24 row_ror:8 row_mask:0xf bank_mask:0xf bound_ctrl:1
	ds_read_b128 v[76:79], v34 offset:0
	s_nop 0
	v_add_f32_dpp v15, v15, v15 row_ror:4 row_mask:0xf bank_mask:0xf bound_ctrl:1
	ds_read_b128 v[128:131], v48 offset:32000
	ds_read_b128 v[132:135], v48 offset:32256
	v_add_f32_dpp v15, v15, v15 row_ror:2 row_mask:0xf bank_mask:0xf bound_ctrl:1
	ds_read_b128 v[136:139], v48 offset:32512
	s_nop 0
	v_add_f32_dpp v30, v15, v15 row_ror:1 row_mask:0xf bank_mask:0xf bound_ctrl:1
	v_pk_fma_f32 v[10:11], v[96:97], v[30:31], v[16:17] op_sel_hi:[1,0,1] neg_lo:[0,1,0] neg_hi:[0,1,0]
	v_pk_fma_f32 v[8:9], v[98:99], v[30:31], v[18:19] op_sel_hi:[1,0,1] neg_lo:[0,1,0] neg_hi:[0,1,0]
	v_pk_mul_f32 v[26:27], v[10:11], v[100:101] op_sel:[0,0] op_sel_hi:[0,1]
	v_pk_fma_f32 v[26:27], v[10:11], v[102:103], v[26:27] op_sel:[1,0,0] op_sel_hi:[1,1,1]
	v_pk_fma_f32 v[26:27], v[8:9], v[104:105], v[26:27] op_sel:[0,0,0] op_sel_hi:[0,1,1]
	v_pk_fma_f32 v[26:27], v[8:9], v[106:107], v[26:27] op_sel:[1,0,0] op_sel_hi:[1,1,1]
	v_pk_fma_f32 v[16:17], v[108:109], v[162:163], v[10:11] op_sel_hi:[1,0,1]
	v_pk_fma_f32 v[18:19], v[110:111], v[162:163], v[8:9] op_sel_hi:[1,0,1]
	v_add_f32_dpp v15, v26, v26 row_ror:8 row_mask:0xf bank_mask:0xf bound_ctrl:1
	ds_read_b128 v[92:95], v34 offset:1024
	s_nop 0
	v_add_f32_dpp v15, v15, v15 row_ror:4 row_mask:0xf bank_mask:0xf bound_ctrl:1
	ds_read_b128 v[80:83], v34 offset:256
	ds_read_b128 v[84:87], v34 offset:512
	v_add_f32_dpp v15, v15, v15 row_ror:2 row_mask:0xf bank_mask:0xf bound_ctrl:1
	ds_read_b128 v[88:91], v34 offset:768
	ds_read_b128 v[144:147], v34 offset:32768
	ds_write2st64_b32 v50, v25, v27 offset0:112 offset1:116
	v_add_f32_dpp v30, v15, v15 row_ror:1 row_mask:0xf bank_mask:0xf bound_ctrl:1
	ds_read_b128 v[156:159], v35 offset:0
	s_waitcnt lgkmcnt(7)
	v_pk_fma_f32 v[10:11], v[112:113], v[30:31], v[16:17] op_sel_hi:[1,0,1] neg_lo:[0,1,0] neg_hi:[0,1,0]
	v_pk_fma_f32 v[8:9], v[114:115], v[30:31], v[18:19] op_sel_hi:[1,0,1] neg_lo:[0,1,0] neg_hi:[0,1,0]
	v_pk_mul_f32 v[24:25], v[10:11], v[116:117] op_sel:[0,0] op_sel_hi:[0,1]
	v_pk_fma_f32 v[24:25], v[10:11], v[118:119], v[24:25] op_sel:[1,0,0] op_sel_hi:[1,1,1]
	v_pk_fma_f32 v[24:25], v[8:9], v[120:121], v[24:25] op_sel:[0,0,0] op_sel_hi:[0,1,1]
	v_pk_fma_f32 v[24:25], v[8:9], v[122:123], v[24:25] op_sel:[1,0,0] op_sel_hi:[1,1,1]
	v_pk_fma_f32 v[16:17], v[124:125], v[162:163], v[10:11] op_sel:[0,1,0] op_sel_hi:[1,1,1]
	v_pk_fma_f32 v[18:19], v[126:127], v[162:163], v[8:9] op_sel:[0,1,0] op_sel_hi:[1,1,1]
	v_add_f32_dpp v15, v24, v24 row_ror:8 row_mask:0xf bank_mask:0xf bound_ctrl:1
	ds_read_b128 v[108:111], v34 offset:2048
	s_nop 0
	v_add_f32_dpp v15, v15, v15 row_ror:4 row_mask:0xf bank_mask:0xf bound_ctrl:1
	ds_read_b128 v[96:99], v34 offset:1280
	ds_read_b128 v[100:103], v34 offset:1536
	v_add_f32_dpp v15, v15, v15 row_ror:2 row_mask:0xf bank_mask:0xf bound_ctrl:1
	ds_read_b128 v[104:107], v34 offset:1792
	s_nop 0
	v_add_f32_dpp v30, v15, v15 row_ror:1 row_mask:0xf bank_mask:0xf bound_ctrl:1
	v_pk_fma_f32 v[10:11], v[128:129], v[30:31], v[16:17] op_sel_hi:[1,0,1] neg_lo:[0,1,0] neg_hi:[0,1,0]
	v_pk_fma_f32 v[8:9], v[130:131], v[30:31], v[18:19] op_sel_hi:[1,0,1] neg_lo:[0,1,0] neg_hi:[0,1,0]
	v_pk_mul_f32 v[26:27], v[10:11], v[132:133] op_sel:[0,0] op_sel_hi:[0,1]
	v_pk_fma_f32 v[26:27], v[10:11], v[134:135], v[26:27] op_sel:[1,0,0] op_sel_hi:[1,1,1]
	v_pk_fma_f32 v[26:27], v[8:9], v[136:137], v[26:27] op_sel:[0,0,0] op_sel_hi:[0,1,1]
	v_pk_fma_f32 v[26:27], v[8:9], v[138:139], v[26:27] op_sel:[1,0,0] op_sel_hi:[1,1,1]
	ds_write2st64_b32 v50, v25, v27 offset0:120 offset1:124
	v_pk_mul_f32 v[10:11], v[10:11], v[140:141]
	v_pk_mul_f32 v[8:9], v[8:9], v[142:143]
	s_waitcnt lgkmcnt(7)
	v_pk_mul_f32 v[24:25], v[10:11], v[144:145]
	v_pk_fma_f32 v[24:25], v[8:9], v[146:147], v[24:25]
	v_add_f32_e32 v24, v24, v25
	s_waitcnt lgkmcnt(5)
	v_pk_fma_f32 v[16:17], v[76:77], v[156:157], v[10:11] op_sel_hi:[1,0,1]
	v_pk_fma_f32 v[18:19], v[78:79], v[156:157], v[8:9] op_sel_hi:[1,0,1]
	v_add_f32_dpp v15, v24, v24 row_ror:8 row_mask:0xf bank_mask:0xf bound_ctrl:1
	v_add_u32_e32 v51, 1, v51
	s_add_u32 s6, s6, 1
	v_add_f32_dpp v15, v15, v15 row_ror:4 row_mask:0xf bank_mask:0xf bound_ctrl:1
	ds_write_b32 v53, v51
	ds_read_b128 v[124:127], v34 offset:3072
	v_add_f32_dpp v15, v15, v15 row_ror:2 row_mask:0xf bank_mask:0xf bound_ctrl:1
	ds_read_b128 v[112:115], v34 offset:2304
	ds_read_b128 v[116:119], v34 offset:2560
	v_add_f32_dpp v30, v15, v15 row_ror:1 row_mask:0xf bank_mask:0xf bound_ctrl:1
	ds_read_b128 v[120:123], v34 offset:2816
	s_cmp_lt_u32 s6, 0x100
	s_cbranch_scc1 .Lsc_S_loop
	s_waitcnt lgkmcnt(0)
	s_branch .Lsc_item_end
	s_nop 0
	s_nop 0
	s_nop 0
	s_nop 0
	s_nop 0
	s_nop 0
	s_nop 0
	s_nop 0
	s_nop 0
	s_nop 0
	s_nop 0
	s_nop 0
	s_nop 0
	s_nop 0
	s_nop 0
	s_nop 0
	s_nop 0
